# LRU: fold -log2e/log2e into pre-scaled gate constants (v_fmamk), re-derived hazard nops in gate sections, conv stage rewritten (11 LDS reads issued together, 8 consecutive tokens per thread)
# speedup vs baseline: 1.0100x; 1.0015x over previous
; template <int PASS>
; __device__ void lru_items(const Params& p, unsigned char* shm, int l) {
;     ...
;         *(u32x4*)(xraw + (tid >> 3) * 64 + (tid & 7) * 8) = xr0;
;         if (tid < 24) *(u32x4*)(xraw + (64 + (tid >> 3)) * 64 + (tid & 7) * 8) = xr1;
;         if (n != n_loaded) {
;             n_loaded = n;
; #pragma unroll
;             for (int i = 0; i < 4; ++i) { const int e = tid + 512 * i, mtx = e >> 9, rem = e & 511, j = rem >> 3, c8 = rem & 7;
;                 *(u32x4*)(wt + (mtx * 64 + j) * 72 + c8 * 8) = *(const u32x4*)(LWT + ((size_t)(mtx * 16 + n) * 64 + j) * 64 + c8 * 8); }
;             { const int ch = n * 64 + (tid & 63); c0 = cw[ch]; c1 = cw[1024 + ch]; c2 = cw[2048 + ch]; c3 = cw[3072 + ch]; cb = cbias[ch]; }
; #pragma unroll
;             for (int jt = 0; jt < 4; ++jt) { const int pi = (l * 2 + (w >> 2)) * 1024 + n * 64 + jt * 16 + fr; gba[jt] = p.in[7][pi]; gbx[jt] = p.in[9][pi]; gsp[jt] = -8.0f * log1pf(__expf(-p.in[10][pi])); }
.LBB0_200:
	s_waitcnt vmcnt(0)
	ds_write_b128 v44, v[2:5]
	s_and_saveexec_b64 s[0:1], s[36:37]
	ds_write_b128 v44, v[6:9] offset:8192
	s_or_b64 exec, exec, s[0:1]
	s_and_b32 s4, s2, 15
	s_cmp_lg_u32 s4, s5
	s_mov_b64 s[0:1], -1
	s_cbranch_scc0 .LBB0_204
	v_or_b32_e32 v10, s4, v52
	v_or_b32_e32 v12, s4, v53
	s_lshl_b32 s48, s4, 6
	v_ashrrev_i32_e32 v11, 31, v10
	v_ashrrev_i32_e32 v13, 31, v12
	v_or_b32_e32 v22, s48, v45
	v_lshlrev_b64 v[10:11], 13, v[10:11]
	v_lshlrev_b64 v[12:13], 13, v[12:13]
	v_ashrrev_i32_e32 v23, 31, v22
	s_mov_b32 s0, s80
	s_mov_b32 s1, s92
	v_readlane_b32 s80, v251, 36
	v_lshl_add_u64 v[10:11], v[28:29], 0, v[10:11]
	v_lshl_add_u64 v[14:15], v[28:29], 0, v[12:13]
	v_lshlrev_b64 v[32:33], 2, v[22:23]
	v_readlane_b32 s84, v251, 40
	v_readlane_b32 s85, v251, 41
	global_load_dwordx4 v[10:13], v[10:11], off
	s_nop 0
	global_load_dwordx4 v[14:17], v[14:15], off
	v_lshl_add_u64 v[40:41], s[84:85], 0, v[32:33]
	global_load_dword v155, v[40:41], off
	global_load_dword v158, v[40:41], off offset:64
	v_or_b32_e32 v18, s4, v54
	v_or_b32_e32 v20, s4, v55
	v_ashrrev_i32_e32 v19, 31, v18
	v_ashrrev_i32_e32 v21, 31, v20
	v_lshlrev_b64 v[18:19], 13, v[18:19]
	v_lshlrev_b64 v[20:21], 13, v[20:21]
	v_lshl_add_u64 v[18:19], v[28:29], 0, v[18:19]
	v_lshl_add_u64 v[22:23], v[28:29], 0, v[20:21]
	global_load_dwordx4 v[18:21], v[18:19], off
	s_nop 0
	global_load_dwordx4 v[22:25], v[22:23], off
	v_or_b32_e32 v0, s48, v43
	v_lshlrev_b32_e32 v0, 2, v0
	s_mov_b32 s80, s0
	s_movk_i32 s0, 0x2000
	v_lshl_add_u64 v[38:39], s[60:61], 0, v[0:1]
	v_add_co_u32_e32 v152, vcc, s0, v38
	s_movk_i32 s0, 0x3000
	s_nop 0
	v_addc_co_u32_e32 v153, vcc, 0, v39, vcc
	v_add_co_u32_e32 v156, vcc, s0, v38
	global_load_dword v151, v0, s[60:61]
	global_load_dword v150, v0, s[62:63]
	v_addc_co_u32_e32 v157, vcc, 0, v39, vcc
	global_load_dword v154, v[152:153], off offset:-4096
	s_nop 0
	global_load_dword v153, v[152:153], off
	s_nop 0
	global_load_dword v152, v[156:157], off
	global_load_dword v0, v[40:41], off offset:128
	global_load_dword v180, v[40:41], off offset:192
	s_mov_b32 s0, 0x3f2aaaab
	s_mov_b32 s6, 0x3ecc95a3
	s_mov_b32 s8, 0x3e9b6dac
	s_mov_b32 s10, 0x3f2aaada
	s_mov_b32 s18, 0x3f317218
	s_mov_b32 s22, 0xb102e308
	v_readlane_b32 s92, v251, 48
	s_mov_b32 s92, s1
	s_mov_b32 s1, 0x7f800000
	s_mov_b32 s28, 0xc1000000
	v_readlane_b32 s64, v251, 20
	v_readlane_b32 s82, v251, 38
	v_readlane_b32 s83, v251, 39
	v_readlane_b32 s78, v251, 34
	v_readlane_b32 s79, v251, 35
	v_readlane_b32 s88, v251, 44
	v_readlane_b32 s89, v251, 45
	v_lshl_add_u64 v[38:39], s[78:79], 0, v[32:33]
	v_lshl_add_u64 v[32:33], s[82:83], 0, v[32:33]
	v_readlane_b32 s90, v251, 46
	v_readlane_b32 s91, v251, 47
	v_readlane_b32 s93, v251, 49
	v_readlane_b32 s94, v251, 50
	v_readlane_b32 s95, v251, 51
	v_readlane_b32 s88, v254, 27
	v_readlane_b32 s90, v254, 25
	v_readlane_b32 s81, v251, 37
	v_readlane_b32 s86, v251, 42
	v_readlane_b32 s87, v251, 43
	s_movk_i32 s94, 0x1000
	s_movk_i32 s95, 0x600
	v_readlane_b32 s89, v254, 28
	v_readlane_b32 s91, v254, 26
	v_readlane_b32 s93, v254, 24
	v_readlane_b32 s84, v254, 58
	v_readlane_b32 s65, v251, 21
	v_readlane_b32 s66, v251, 22
	v_readlane_b32 s67, v251, 23
	v_readlane_b32 s68, v251, 24
	s_waitcnt vmcnt(12)
	ds_write_b128 v143, v[10:13] offset:34560
	s_waitcnt vmcnt(11)
	ds_write_b128 v144, v[14:17] offset:34560
	s_waitcnt vmcnt(10)
	v_mul_f32_e32 v10, 0xbfb8aa3b, v155
	v_exp_f32_e32 v155, v10
	s_waitcnt vmcnt(9)
	v_mul_f32_e32 v11, 0xbfb8aa3b, v158
	v_exp_f32_e32 v158, v11
	s_waitcnt vmcnt(8)
	ds_write_b128 v145, v[18:21] offset:34560
	s_waitcnt vmcnt(7)
	ds_write_b128 v146, v[22:25] offset:34560
	v_add_f32_e32 v14, 1.0, v155
	v_frexp_mant_f32_e32 v17, v14
	v_cvt_f64_f32_e32 v[10:11], v14
	v_add_f32_e32 v15, 1.0, v158
	v_frexp_exp_i32_f64_e32 v10, v[10:11]
	v_cmp_gt_f32_e32 vcc, s0, v17
	v_add_f32_e32 v16, -1.0, v14
	v_frexp_mant_f32_e32 v19, v15
	v_cvt_f64_f32_e32 v[12:13], v15
	v_subbrev_co_u32_e32 v172, vcc, 0, v10, vcc
	v_add_f32_e32 v18, -1.0, v15
	v_sub_f32_e32 v20, v16, v14
	v_frexp_exp_i32_f64_e32 v12, v[12:13]
	v_cmp_gt_f32_e32 vcc, s0, v19
	v_sub_f32_e32 v16, v155, v16
	v_sub_f32_e32 v11, v18, v15
	v_add_f32_e32 v13, 1.0, v20
	v_subbrev_co_u32_e32 v173, vcc, 0, v12, vcc
	v_sub_f32_e32 v18, v158, v18
	v_add_f32_e32 v10, 1.0, v11
	v_add_f32_e32 v12, v16, v13
	v_sub_u32_e32 v13, 0, v172
	v_sub_u32_e32 v17, 0, v173
	v_add_f32_e32 v16, v18, v10
	v_ldexp_f32 v11, v14, v13
	v_ldexp_f32 v10, v15, v17
	v_pk_add_f32 v[14:15], v[10:11], 1.0 op_sel_hi:[1,0]
	v_ldexp_f32 v13, v12, v13
	v_ldexp_f32 v12, v16, v17
	v_pk_add_f32 v[16:17], v[10:11], -1.0 op_sel_hi:[1,0]
	v_pk_add_f32 v[18:19], v[14:15], -1.0 op_sel_hi:[1,0]
	v_pk_add_f32 v[20:21], v[16:17], 1.0 op_sel_hi:[1,0]
	v_pk_add_f32 v[18:19], v[10:11], v[18:19] neg_lo:[0,1] neg_hi:[0,1]
	v_pk_add_f32 v[10:11], v[10:11], v[20:21] neg_lo:[0,1] neg_hi:[0,1]
	v_pk_add_f32 v[18:19], v[12:13], v[18:19]
	v_pk_add_f32 v[10:11], v[12:13], v[10:11]
	v_pk_add_f32 v[12:13], v[14:15], v[18:19]
	v_pk_add_f32 v[20:21], v[16:17], v[10:11]
	v_rcp_f32_e32 v23, v13
	v_rcp_f32_e32 v22, v12
	v_pk_add_f32 v[16:17], v[20:21], v[16:17] neg_lo:[0,1] neg_hi:[0,1]
	v_pk_add_f32 v[14:15], v[12:13], v[14:15] neg_lo:[0,1] neg_hi:[0,1]
	v_pk_add_f32 v[10:11], v[10:11], v[16:17] neg_lo:[0,1] neg_hi:[0,1]
	v_pk_mul_f32 v[16:17], v[20:21], v[22:23]
	v_pk_add_f32 v[14:15], v[18:19], v[14:15] neg_lo:[0,1] neg_hi:[0,1]
	v_pk_mul_f32 v[18:19], v[12:13], v[16:17]
	v_cmp_neq_f32_e32 vcc, s1, v158
	v_pk_fma_f32 v[24:25], v[16:17], v[12:13], v[18:19] neg_lo:[0,0,1] neg_hi:[0,0,1]
	s_waitcnt vmcnt(1)
; template <int PASS>
; __device__ void lru_items(const Params& p, unsigned char* shm, int l) {
;     ...
;             { const int ch = n * 64 + (tid & 63); c0 = cw[ch]; c1 = cw[1024 + ch]; c2 = cw[2048 + ch]; c3 = cw[3072 + ch]; cb = cbias[ch]; }
; #pragma unroll
;             for (int jt = 0; jt < 4; ++jt) { const int pi = (l * 2 + (w >> 2)) * 1024 + n * 64 + jt * 16 + fr; gba[jt] = p.in[7][pi]; gbx[jt] = p.in[9][pi]; gsp[jt] = -8.0f * log1pf(__expf(-p.in[10][pi])); }
	v_mul_f32_e32 v0, 0xbfb8aa3b, v0
	v_pk_fma_f32 v[24:25], v[16:17], v[14:15], v[24:25]
	v_exp_f32_e32 v0, v0
	v_pk_add_f32 v[40:41], v[18:19], v[24:25]
	v_readlane_b32 s69, v251, 25
	v_pk_add_f32 v[156:157], v[20:21], v[40:41] neg_lo:[0,1] neg_hi:[0,1]
	v_pk_add_f32 v[18:19], v[40:41], v[18:19] neg_lo:[0,1] neg_hi:[0,1]
	v_pk_add_f32 v[20:21], v[20:21], v[156:157] neg_lo:[0,1] neg_hi:[0,1]
	v_pk_add_f32 v[18:19], v[18:19], v[24:25] neg_lo:[0,1] neg_hi:[0,1]
	v_pk_add_f32 v[20:21], v[20:21], v[40:41] neg_lo:[0,1] neg_hi:[0,1]
	v_readlane_b32 s70, v251, 26
	v_pk_add_f32 v[10:11], v[10:11], v[20:21]
	v_readlane_b32 s71, v251, 27
	v_pk_add_f32 v[10:11], v[18:19], v[10:11]
	v_readlane_b32 s72, v251, 28
	v_pk_add_f32 v[18:19], v[156:157], v[10:11]
	v_readlane_b32 s73, v251, 29
	v_pk_mul_f32 v[20:21], v[22:23], v[18:19]
	v_pk_add_f32 v[24:25], v[156:157], v[18:19] neg_lo:[0,1] neg_hi:[0,1]
	v_pk_mul_f32 v[40:41], v[12:13], v[20:21]
	v_pk_add_f32 v[10:11], v[10:11], v[24:25]
	v_pk_fma_f32 v[12:13], v[20:21], v[12:13], v[40:41] neg_lo:[0,0,1] neg_hi:[0,0,1]
	v_readlane_b32 s74, v251, 30
	v_pk_fma_f32 v[12:13], v[20:21], v[14:15], v[12:13]
	v_readlane_b32 s75, v251, 31
	v_pk_add_f32 v[14:15], v[40:41], v[12:13]
	v_readlane_b32 s76, v251, 32
	v_pk_add_f32 v[24:25], v[14:15], v[40:41] neg_lo:[0,1] neg_hi:[0,1]
	v_pk_add_f32 v[40:41], v[18:19], v[14:15] neg_lo:[0,1] neg_hi:[0,1]
	v_pk_add_f32 v[12:13], v[24:25], v[12:13] neg_lo:[0,1] neg_hi:[0,1]
	v_pk_add_f32 v[18:19], v[18:19], v[40:41] neg_lo:[0,1] neg_hi:[0,1]
	v_readlane_b32 s77, v251, 33
	v_pk_add_f32 v[14:15], v[18:19], v[14:15] neg_lo:[0,1] neg_hi:[0,1]
	v_mov_b64_e32 v[18:19], s[6:7]
	v_pk_add_f32 v[10:11], v[10:11], v[14:15]
	s_mov_b32 s6, 0x33800000
	v_pk_add_f32 v[10:11], v[12:13], v[10:11]
	v_pk_add_f32 v[12:13], v[16:17], v[20:21]
	v_pk_add_f32 v[10:11], v[40:41], v[10:11]
	v_pk_add_f32 v[14:15], v[12:13], v[16:17] neg_lo:[0,1] neg_hi:[0,1]
	v_pk_mul_f32 v[10:11], v[22:23], v[10:11]
	v_pk_add_f32 v[14:15], v[20:21], v[14:15] neg_lo:[0,1] neg_hi:[0,1]
	v_cvt_f32_i32_e32 v23, v172
	v_pk_add_f32 v[10:11], v[14:15], v[10:11]
	v_cvt_f32_i32_e32 v22, v173
	v_pk_add_f32 v[14:15], v[12:13], v[10:11]
	s_movk_i32 s82, 0x60
	v_pk_mul_f32 v[16:17], v[14:15], v[14:15]
	v_pk_add_f32 v[12:13], v[14:15], v[12:13] neg_lo:[0,1] neg_hi:[0,1]
	v_pk_fma_f32 v[20:21], v[16:17], s[8:9], v[18:19] op_sel_hi:[1,0,0]
	v_pk_add_f32 v[10:11], v[10:11], v[12:13] neg_lo:[0,1] neg_hi:[0,1]
	v_ldexp_f32 v13, v15, 1
	v_pk_fma_f32 v[20:21], v[16:17], v[20:21], s[10:11] op_sel_hi:[1,1,0]
	v_ldexp_f32 v12, v14, 1
	v_pk_mul_f32 v[14:15], v[14:15], v[16:17]
	v_pk_mul_f32 v[16:17], v[22:23], s[18:19] op_sel_hi:[1,0]
	v_pk_mul_f32 v[14:15], v[14:15], v[20:21]
	v_pk_fma_f32 v[40:41], v[22:23], s[18:19], v[16:17] op_sel_hi:[1,0,1] neg_lo:[0,0,1] neg_hi:[0,0,1]
	v_pk_add_f32 v[20:21], v[12:13], v[14:15]
	v_ldexp_f32 v11, v11, 1
	v_pk_add_f32 v[12:13], v[20:21], v[12:13] neg_lo:[0,1] neg_hi:[0,1]
	v_pk_fma_f32 v[22:23], v[22:23], s[22:23], v[40:41] op_sel_hi:[1,0,1]
	v_pk_add_f32 v[12:13], v[14:15], v[12:13] neg_lo:[0,1] neg_hi:[0,1]
	v_ldexp_f32 v24, v10, 1
	v_mov_b32_e32 v14, v16
	v_mov_b32_e32 v15, v13
	v_mov_b32_e32 v10, v22
	v_mov_b32_e32 v25, v11
	v_pk_add_f32 v[14:15], v[14:15], v[10:11]
	v_pk_add_f32 v[10:11], v[24:25], v[12:13]
	v_mov_b32_e32 v13, v21
	v_mov_b32_e32 v25, v11
	v_pk_add_f32 v[40:41], v[16:17], v[22:23]
	v_pk_add_f32 v[12:13], v[24:25], v[12:13]
	v_pk_add_f32 v[24:25], v[20:21], v[10:11]
	v_mov_b32_e32 v174, v20
	v_pk_add_f32 v[156:157], v[40:41], v[24:25]
	v_mov_b32_e32 v172, v24
	v_mov_b32_e32 v173, v157
	v_mov_b32_e32 v175, v41
	v_pk_add_f32 v[172:173], v[172:173], v[174:175] neg_lo:[0,1] neg_hi:[0,1]
	v_mov_b32_e32 v174, v40
	v_mov_b32_e32 v175, v157
	v_mov_b32_e32 v176, v16
	v_mov_b32_e32 v177, v173
	v_pk_add_f32 v[174:175], v[174:175], v[176:177] neg_lo:[0,1] neg_hi:[0,1]
	v_mov_b32_e32 v177, v41
	v_mov_b32_e32 v178, v156
	v_mov_b32_e32 v179, v41
	v_mov_b32_e32 v41, v17
	v_mov_b32_e32 v176, v22
	v_pk_add_f32 v[16:17], v[178:179], v[40:41] neg_lo:[0,1] neg_hi:[0,1]
	v_pk_add_f32 v[176:177], v[176:177], v[174:175] neg_lo:[0,1] neg_hi:[0,1]
	v_mov_b32_e32 v175, v17
	v_pk_add_f32 v[40:41], v[22:23], v[174:175] neg_lo:[0,1] neg_hi:[0,1]
	v_pk_add_f32 v[174:175], v[24:25], v[20:21] neg_lo:[0,1] neg_hi:[0,1]
	v_pk_add_f32 v[12:13], v[12:13], v[172:173] neg_lo:[0,1] neg_hi:[0,1]
	v_mov_b32_e32 v172, v156
	v_mov_b32_e32 v173, v25
	v_mov_b32_e32 v20, v16
	v_pk_add_f32 v[20:21], v[172:173], v[20:21] neg_lo:[0,1] neg_hi:[0,1]
	v_mov_b32_e32 v25, v23
	v_pk_add_f32 v[14:15], v[14:15], v[20:21] neg_lo:[0,1] neg_hi:[0,1]
	v_pk_add_f32 v[16:17], v[24:25], v[16:17] neg_lo:[0,1] neg_hi:[0,1]
	v_pk_add_f32 v[22:23], v[12:13], v[176:177]
	v_mov_b32_e32 v177, v17
	v_mov_b32_e32 v13, v15
	v_pk_add_f32 v[20:21], v[16:17], v[14:15]
	v_pk_add_f32 v[12:13], v[176:177], v[12:13]
	v_mov_b32_e32 v14, v22
	v_pk_add_f32 v[12:13], v[12:13], v[40:41] neg_lo:[0,1] neg_hi:[0,1]
	v_mov_b32_e32 v15, v21
	v_pk_add_f32 v[10:11], v[10:11], v[174:175] neg_lo:[0,1] neg_hi:[0,1]
	v_pk_add_f32 v[14:15], v[14:15], v[12:13] neg_lo:[0,1] neg_hi:[0,1]
	v_pk_add_f32 v[10:11], v[10:11], v[12:13] neg_lo:[0,1] neg_hi:[0,1]
	v_pk_add_f32 v[14:15], v[176:177], v[14:15] neg_lo:[0,1] neg_hi:[0,1]
	v_pk_add_f32 v[12:13], v[20:21], v[22:23]
	v_pk_add_f32 v[10:11], v[10:11], v[14:15]
	v_pk_add_f32 v[14:15], v[156:157], v[12:13]
	s_nop 0
	v_pk_add_f32 v[16:17], v[14:15], v[156:157] neg_lo:[0,1] neg_hi:[0,1]
	s_nop 0
	v_pk_add_f32 v[12:13], v[12:13], v[16:17] neg_lo:[0,1] neg_hi:[0,1]
	s_nop 0
	v_pk_add_f32 v[10:11], v[10:11], v[12:13]
	v_add_f32_e32 v12, 1.0, v0
	v_pk_add_f32 v[10:11], v[14:15], v[10:11]
	v_frexp_mant_f32_e32 v14, v12
	v_cndmask_b32_e32 v10, v237, v10, vcc
	v_cmp_neq_f32_e32 vcc, s1, v155
	s_nop 1
	v_cndmask_b32_e32 v11, v237, v11, vcc
	v_cmp_ngt_f32_e32 vcc, -1.0, v155
	s_nop 1
	v_cndmask_b32_e32 v11, v238, v11, vcc
	v_cmp_ngt_f32_e32 vcc, -1.0, v158
	s_nop 1
	v_cndmask_b32_e32 v10, v238, v10, vcc
	v_cmp_neq_f32_e32 vcc, -1.0, v158
	s_nop 1
	v_cndmask_b32_e32 v10, v239, v10, vcc
	v_cmp_neq_f32_e32 vcc, -1.0, v155
	s_nop 1
	v_cndmask_b32_e32 v11, v239, v11, vcc
	v_cmp_lt_f32_e64 vcc, |v155|, s6
	s_nop 1
	v_cndmask_b32_e32 v11, v11, v155, vcc
	v_cmp_lt_f32_e64 vcc, |v158|, s6
	s_nop 1
	v_cndmask_b32_e32 v10, v10, v158, vcc
	v_pk_mul_f32 v[22:23], v[10:11], s[28:29] op_sel_hi:[1,0]
	v_add_f32_e32 v10, -1.0, v12
	v_sub_f32_e32 v11, v10, v12
	v_add_f32_e32 v11, 1.0, v11
	v_sub_f32_e32 v10, v0, v10
	v_add_f32_e32 v13, v10, v11
	v_cvt_f64_f32_e32 v[10:11], v12
	v_frexp_exp_i32_f64_e32 v10, v[10:11]
	v_cmp_gt_f32_e32 vcc, s0, v14
	global_load_dword v157, v[38:39], off
	global_load_dword v158, v[38:39], off offset:64
	global_load_dword v40, v[38:39], off offset:128
	global_load_dword v41, v[38:39], off offset:192
	v_subbrev_co_u32_e32 v178, vcc, 0, v10, vcc
	v_sub_u32_e32 v10, 0, v178
	v_ldexp_f32 v11, v12, v10
	v_ldexp_f32 v13, v13, v10
	s_waitcnt vmcnt(4)
; template <int PASS>
; __device__ void lru_items(const Params& p, unsigned char* shm, int l) {
;     ...
;             for (int jt = 0; jt < 4; ++jt) { const int pi = (l * 2 + (w >> 2)) * 1024 + n * 64 + jt * 16 + fr; gba[jt] = p.in[7][pi]; gbx[jt] = p.in[9][pi]; gsp[jt] = -8.0f * log1pf(__expf(-p.in[10][pi])); }
	v_mul_f32_e32 v10, 0xbfb8aa3b, v180
	v_exp_f32_e32 v182, v10
	global_load_dword v155, v[32:33], off
	global_load_dword v156, v[32:33], off offset:64
	global_load_dword v38, v[32:33], off offset:128
	global_load_dword v39, v[32:33], off offset:192
	v_add_f32_e32 v10, 1.0, v182
	v_add_f32_e32 v12, -1.0, v10
	v_sub_f32_e32 v14, v12, v10
	v_add_f32_e32 v14, 1.0, v14
	v_sub_f32_e32 v12, v182, v12
	v_add_f32_e32 v12, v12, v14
	v_frexp_mant_f32_e32 v16, v10
	v_cvt_f64_f32_e32 v[14:15], v10
	v_frexp_exp_i32_f64_e32 v14, v[14:15]
	v_cmp_gt_f32_e32 vcc, s0, v16
	s_nop 1
	v_subbrev_co_u32_e32 v179, vcc, 0, v14, vcc
	v_sub_u32_e32 v14, 0, v179
	v_ldexp_f32 v10, v10, v14
	v_ldexp_f32 v12, v12, v14
	v_pk_add_f32 v[14:15], v[10:11], 1.0 op_sel_hi:[1,0]
	v_pk_add_f32 v[32:33], v[10:11], -1.0 op_sel_hi:[1,0]
	v_pk_add_f32 v[16:17], v[14:15], -1.0 op_sel_hi:[1,0]
	v_pk_add_f32 v[172:173], v[32:33], 1.0 op_sel_hi:[1,0]
	v_pk_add_f32 v[16:17], v[10:11], v[16:17] neg_lo:[0,1] neg_hi:[0,1]
	v_pk_add_f32 v[10:11], v[10:11], v[172:173] neg_lo:[0,1] neg_hi:[0,1]
	v_pk_add_f32 v[16:17], v[12:13], v[16:17]
	v_pk_add_f32 v[10:11], v[12:13], v[10:11]
	v_pk_add_f32 v[20:21], v[14:15], v[16:17]
	v_pk_add_f32 v[12:13], v[32:33], v[10:11]
	v_rcp_f32_e32 v25, v21
	v_rcp_f32_e32 v24, v20
	v_pk_add_f32 v[14:15], v[20:21], v[14:15] neg_lo:[0,1] neg_hi:[0,1]
	v_pk_add_f32 v[32:33], v[12:13], v[32:33] neg_lo:[0,1] neg_hi:[0,1]
	v_pk_add_f32 v[14:15], v[16:17], v[14:15] neg_lo:[0,1] neg_hi:[0,1]
	v_pk_mul_f32 v[16:17], v[12:13], v[24:25]
	v_pk_add_f32 v[10:11], v[10:11], v[32:33] neg_lo:[0,1] neg_hi:[0,1]
	v_pk_mul_f32 v[32:33], v[20:21], v[16:17]
	v_cmp_neq_f32_e32 vcc, s1, v182
	v_pk_fma_f32 v[172:173], v[16:17], v[20:21], v[32:33] neg_lo:[0,0,1] neg_hi:[0,0,1]
	s_nop 0
	v_pk_fma_f32 v[172:173], v[16:17], v[14:15], v[172:173]
	s_nop 0
	v_pk_add_f32 v[174:175], v[32:33], v[172:173]
	s_nop 0
	v_pk_add_f32 v[176:177], v[12:13], v[174:175] neg_lo:[0,1] neg_hi:[0,1]
	v_pk_add_f32 v[32:33], v[174:175], v[32:33] neg_lo:[0,1] neg_hi:[0,1]
	v_pk_add_f32 v[12:13], v[12:13], v[176:177] neg_lo:[0,1] neg_hi:[0,1]
	s_nop 0
	v_pk_add_f32 v[12:13], v[12:13], v[174:175] neg_lo:[0,1] neg_hi:[0,1]
	s_nop 0
	v_pk_add_f32 v[10:11], v[10:11], v[12:13]
	v_pk_add_f32 v[12:13], v[32:33], v[172:173] neg_lo:[0,1] neg_hi:[0,1]
	s_nop 0
	v_pk_add_f32 v[10:11], v[12:13], v[10:11]
	s_nop 0
	v_pk_add_f32 v[12:13], v[176:177], v[10:11]
	s_nop 0
	v_pk_mul_f32 v[32:33], v[24:25], v[12:13]
	s_nop 0
	v_pk_mul_f32 v[172:173], v[20:21], v[32:33]
	s_nop 0
	v_pk_fma_f32 v[20:21], v[32:33], v[20:21], v[172:173] neg_lo:[0,0,1] neg_hi:[0,0,1]
	s_nop 0
	v_pk_fma_f32 v[14:15], v[32:33], v[14:15], v[20:21]
	v_pk_add_f32 v[20:21], v[176:177], v[12:13] neg_lo:[0,1] neg_hi:[0,1]
	s_nop 0
	v_pk_add_f32 v[10:11], v[10:11], v[20:21]
	v_pk_add_f32 v[20:21], v[172:173], v[14:15]
	s_nop 0
	v_pk_add_f32 v[174:175], v[12:13], v[20:21] neg_lo:[0,1] neg_hi:[0,1]
	v_pk_add_f32 v[172:173], v[20:21], v[172:173] neg_lo:[0,1] neg_hi:[0,1]
	v_pk_add_f32 v[12:13], v[12:13], v[174:175] neg_lo:[0,1] neg_hi:[0,1]
	s_nop 0
	v_pk_add_f32 v[12:13], v[12:13], v[20:21] neg_lo:[0,1] neg_hi:[0,1]
	v_cvt_f32_i32_e32 v21, v178
	v_pk_add_f32 v[10:11], v[10:11], v[12:13]
	v_pk_add_f32 v[12:13], v[172:173], v[14:15] neg_lo:[0,1] neg_hi:[0,1]
	v_cvt_f32_i32_e32 v20, v179
	v_pk_add_f32 v[10:11], v[12:13], v[10:11]
	v_pk_add_f32 v[12:13], v[16:17], v[32:33]
	v_pk_add_f32 v[10:11], v[174:175], v[10:11]
	v_pk_add_f32 v[14:15], v[12:13], v[16:17] neg_lo:[0,1] neg_hi:[0,1]
	v_pk_mul_f32 v[10:11], v[24:25], v[10:11]
	v_pk_add_f32 v[14:15], v[32:33], v[14:15] neg_lo:[0,1] neg_hi:[0,1]
	s_nop 0
	v_pk_add_f32 v[10:11], v[14:15], v[10:11]
	s_nop 0
	v_pk_add_f32 v[14:15], v[12:13], v[10:11]
	s_nop 0
	v_pk_mul_f32 v[16:17], v[14:15], v[14:15]
	v_pk_add_f32 v[12:13], v[14:15], v[12:13] neg_lo:[0,1] neg_hi:[0,1]
	v_pk_fma_f32 v[18:19], v[16:17], s[8:9], v[18:19] op_sel_hi:[1,0,0]
	v_pk_add_f32 v[10:11], v[10:11], v[12:13] neg_lo:[0,1] neg_hi:[0,1]
	v_ldexp_f32 v13, v15, 1
	v_pk_fma_f32 v[18:19], v[16:17], v[18:19], s[10:11] op_sel_hi:[1,1,0]
	v_ldexp_f32 v12, v14, 1
	v_pk_mul_f32 v[14:15], v[14:15], v[16:17]
; __device__ __forceinline__ float sigm(float x) { return __builtin_amdgcn_rcpf(1.0f + __expf(-x)); }
; template <int PASS>
; __device__ void lru_items(const Params& p, unsigned char* shm, int l) {
;     ...
;             { const int ch = n * 64 + (tid & 63); c0 = cw[ch]; c1 = cw[1024 + ch]; c2 = cw[2048 + ch]; c3 = cw[3072 + ch]; cb = cbias[ch]; }
; #pragma unroll
;             for (int jt = 0; jt < 4; ++jt) { const int pi = (l * 2 + (w >> 2)) * 1024 + n * 64 + jt * 16 + fr; gba[jt] = p.in[7][pi]; gbx[jt] = p.in[9][pi]; gsp[jt] = -8.0f * log1pf(__expf(-p.in[10][pi])); }
;     ...
;                   const float r = sigm(accr[i] + gba[jt]), ig = sigm(acci[i] + gbx[jt]), a = __expf(r * gsp[jt]);
	v_pk_mul_f32 v[16:17], v[20:21], s[18:19] op_sel_hi:[1,0]
	v_pk_mul_f32 v[14:15], v[14:15], v[18:19]
	v_pk_fma_f32 v[32:33], v[20:21], s[18:19], v[16:17] op_sel_hi:[1,0,1] neg_lo:[0,0,1] neg_hi:[0,0,1]
	v_pk_add_f32 v[18:19], v[12:13], v[14:15]
	v_ldexp_f32 v11, v11, 1
	v_pk_add_f32 v[12:13], v[18:19], v[12:13] neg_lo:[0,1] neg_hi:[0,1]
	v_pk_fma_f32 v[20:21], v[20:21], s[22:23], v[32:33] op_sel_hi:[1,0,1]
	v_pk_add_f32 v[12:13], v[14:15], v[12:13] neg_lo:[0,1] neg_hi:[0,1]
	v_ldexp_f32 v24, v10, 1
	v_mov_b32_e32 v14, v16
	v_mov_b32_e32 v15, v13
	v_mov_b32_e32 v10, v20
	v_mov_b32_e32 v25, v11
	v_pk_add_f32 v[14:15], v[14:15], v[10:11]
	v_pk_add_f32 v[10:11], v[24:25], v[12:13]
	v_mov_b32_e32 v13, v19
	v_mov_b32_e32 v25, v11
	v_pk_add_f32 v[32:33], v[16:17], v[20:21]
	v_pk_add_f32 v[12:13], v[24:25], v[12:13]
	v_pk_add_f32 v[24:25], v[18:19], v[10:11]
	v_mov_b32_e32 v176, v18
	v_pk_add_f32 v[172:173], v[32:33], v[24:25]
	v_mov_b32_e32 v174, v24
	v_mov_b32_e32 v175, v173
	v_mov_b32_e32 v177, v33
	v_pk_add_f32 v[174:175], v[174:175], v[176:177] neg_lo:[0,1] neg_hi:[0,1]
	v_mov_b32_e32 v176, v32
	v_mov_b32_e32 v177, v173
	v_mov_b32_e32 v178, v16
	v_mov_b32_e32 v179, v175
	v_pk_add_f32 v[176:177], v[176:177], v[178:179] neg_lo:[0,1] neg_hi:[0,1]
	v_mov_b32_e32 v179, v33
	v_mov_b32_e32 v180, v172
	v_mov_b32_e32 v181, v33
	v_mov_b32_e32 v33, v17
	v_mov_b32_e32 v178, v20
	v_pk_add_f32 v[16:17], v[180:181], v[32:33] neg_lo:[0,1] neg_hi:[0,1]
	v_pk_add_f32 v[178:179], v[178:179], v[176:177] neg_lo:[0,1] neg_hi:[0,1]
	v_mov_b32_e32 v177, v17
	v_pk_add_f32 v[32:33], v[20:21], v[176:177] neg_lo:[0,1] neg_hi:[0,1]
	v_pk_add_f32 v[176:177], v[24:25], v[18:19] neg_lo:[0,1] neg_hi:[0,1]
	v_pk_add_f32 v[12:13], v[12:13], v[174:175] neg_lo:[0,1] neg_hi:[0,1]
	v_mov_b32_e32 v174, v172
	v_mov_b32_e32 v175, v25
	v_mov_b32_e32 v18, v16
	v_pk_add_f32 v[18:19], v[174:175], v[18:19] neg_lo:[0,1] neg_hi:[0,1]
	v_mov_b32_e32 v25, v21
	v_pk_add_f32 v[14:15], v[14:15], v[18:19] neg_lo:[0,1] neg_hi:[0,1]
	v_pk_add_f32 v[16:17], v[24:25], v[16:17] neg_lo:[0,1] neg_hi:[0,1]
	v_pk_add_f32 v[20:21], v[12:13], v[178:179]
	v_mov_b32_e32 v179, v17
	v_mov_b32_e32 v13, v15
	v_pk_add_f32 v[18:19], v[16:17], v[14:15]
	v_pk_add_f32 v[12:13], v[178:179], v[12:13]
	v_mov_b32_e32 v14, v20
	v_pk_add_f32 v[12:13], v[12:13], v[32:33] neg_lo:[0,1] neg_hi:[0,1]
	v_mov_b32_e32 v15, v19
	v_pk_add_f32 v[10:11], v[10:11], v[176:177] neg_lo:[0,1] neg_hi:[0,1]
	v_pk_add_f32 v[14:15], v[14:15], v[12:13] neg_lo:[0,1] neg_hi:[0,1]
	v_pk_add_f32 v[10:11], v[10:11], v[12:13] neg_lo:[0,1] neg_hi:[0,1]
	v_pk_add_f32 v[14:15], v[178:179], v[14:15] neg_lo:[0,1] neg_hi:[0,1]
	v_pk_add_f32 v[12:13], v[18:19], v[20:21]
	v_pk_add_f32 v[10:11], v[10:11], v[14:15]
	v_pk_add_f32 v[14:15], v[172:173], v[12:13]
	s_nop 0
	v_pk_add_f32 v[16:17], v[14:15], v[172:173] neg_lo:[0,1] neg_hi:[0,1]
	s_nop 0
	v_pk_add_f32 v[12:13], v[12:13], v[16:17] neg_lo:[0,1] neg_hi:[0,1]
	s_nop 0
	v_pk_add_f32 v[10:11], v[10:11], v[12:13]
	s_nop 0
	v_pk_add_f32 v[10:11], v[14:15], v[10:11]
	s_nop 0
	v_cndmask_b32_e32 v10, v237, v10, vcc
	v_cmp_neq_f32_e32 vcc, s1, v0
	s_mov_b64 s[0:1], 0
	s_nop 0
	v_cndmask_b32_e32 v11, v237, v11, vcc
	v_cmp_ngt_f32_e32 vcc, -1.0, v0
	s_nop 1
	v_cndmask_b32_e32 v11, v238, v11, vcc
	v_cmp_ngt_f32_e32 vcc, -1.0, v182
	s_nop 1
	v_cndmask_b32_e32 v10, v238, v10, vcc
	v_cmp_neq_f32_e32 vcc, -1.0, v182
	s_nop 1
	v_cndmask_b32_e32 v10, v239, v10, vcc
	v_cmp_neq_f32_e32 vcc, -1.0, v0
	s_nop 1
	v_cndmask_b32_e32 v11, v239, v11, vcc
	v_cmp_lt_f32_e64 vcc, |v0|, s6
	s_nop 1
	v_cndmask_b32_e32 v11, v11, v0, vcc
	v_cmp_lt_f32_e64 vcc, |v182|, s6
	s_nop 1
	v_cndmask_b32_e32 v10, v10, v182, vcc
	v_pk_mul_f32 v[24:25], v[10:11], s[28:29] op_sel_hi:[1,0]
	s_waitcnt vmcnt(0)
	v_mul_f32_e32 v155, 0xbfb8aa3b, v155
	v_mul_f32_e32 v156, 0xbfb8aa3b, v156
	v_mul_f32_e32 v157, 0xbfb8aa3b, v157
	v_mul_f32_e32 v158, 0xbfb8aa3b, v158
	v_mul_f32_e32 v38, 0xbfb8aa3b, v38
	v_mul_f32_e32 v39, 0xbfb8aa3b, v39
	v_mul_f32_e32 v40, 0xbfb8aa3b, v40
	v_mul_f32_e32 v41, 0xbfb8aa3b, v41
	v_mul_f32_e32 v22, 0x3fb8aa3b, v22
	v_mul_f32_e32 v23, 0x3fb8aa3b, v23
	v_mul_f32_e32 v24, 0x3fb8aa3b, v24
	v_mul_f32_e32 v25, 0x3fb8aa3b, v25

; __device__ __forceinline__ bf16_t f2bf(float f) { return (bf16_t)(cvt_pk_bf16(f, 0.f) & 0xffffu); }
; __device__ __forceinline__ float bf2f(bf16_t b) { return __uint_as_float(((unsigned)b) << 16); }
; __device__ __forceinline__ float sigm(float x) { return __builtin_amdgcn_rcpf(1.0f + __expf(-x)); }
; template <int PASS>
; __device__ void lru_items(const Params& p, unsigned char* shm, int l) {
;     ...
;         { const int j = tid & 63;
; #pragma unroll
;           for (int i = 0; i < 8; ++i) { const int t = (tid >> 6) + 8 * i;
;               const float v = cb + bf2f(xraw[t * 64 + j]) * c0 + bf2f(xraw[(t + 1) * 64 + j]) * c1 + bf2f(xraw[(t + 2) * 64 + j]) * c2 + bf2f(xraw[(t + 3) * 64 + j]) * c3;
;               xcf[t * 65 + j] = v; xcb[t * 72 + j] = f2bf(v); } }
;         __syncthreads();
;         { const int d = w >> 2, tt = w & 3;
;           const bf16x8 a0 = *(const bf16x8*)(xcb + (tt * 16 + fr) * 72 + fq * 8), a1 = *(const bf16x8*)(xcb + (tt * 16 + fr) * 72 + 32 + fq * 8);
; #pragma unroll
;           for (int jt = 0; jt < 4; ++jt) {
;               f32x4 accr = (f32x4){0.f, 0.f, 0.f, 0.f}, acci = (f32x4){0.f, 0.f, 0.f, 0.f};
;               const bf16_t* wr_ = wt + ((d * 2 + 0) * 64 + jt * 16 + fr) * 72 + fq * 8; const bf16_t* wi_ = wt + ((d * 2 + 1) * 64 + jt * 16 + fr) * 72 + fq * 8;
;               accr = __builtin_amdgcn_mfma_f32_16x16x32_bf16(a0, *(const bf16x8*)wr_, accr, 0, 0, 0);
;               accr = __builtin_amdgcn_mfma_f32_16x16x32_bf16(a1, *(const bf16x8*)(wr_ + 32), accr, 0, 0, 0);
;               acci = __builtin_amdgcn_mfma_f32_16x16x32_bf16(a0, *(const bf16x8*)wi_, acci, 0, 0, 0);
;               acci = __builtin_amdgcn_mfma_f32_16x16x32_bf16(a1, *(const bf16x8*)(wi_ + 32), acci, 0, 0, 0);
;               const int j = jt * 16 + fr;
; #pragma unroll
;               for (int i = 0; i < 4; ++i) { const int t = tt * 16 + fq * 4 + i;
;                   const float r = sigm(accr[i] + gba[jt]), ig = sigm(acci[i] + gbx[jt]), a = __expf(r * gsp[jt]);
;                   As[(d * 64 + t) * 64 + j] = a;
;                   Bs[(d * 64 + t) * 64 + j] = sqrtf(fmaxf(1.0f - a * a, 0.f)) * ig * xcf[t * 65 + j]; }
;           } }
.LBB0_214:
	s_mov_b32 s0, 0xf800000
	v_lshrrev_b32_e32 v183, 6, v229
	v_and_b32_e32 v184, 63, v229
	v_lshlrev_b32_e32 v185, 10, v183
	v_lshl_add_u32 v185, v184, 1, v185
	ds_read_u16 v186, v185
	ds_read_u16 v187, v185 offset:128
	ds_read_u16 v188, v185 offset:256
	ds_read_u16 v189, v185 offset:384
	ds_read_u16 v190, v185 offset:512
	ds_read_u16 v191, v185 offset:640
	ds_read_u16 v192, v185 offset:768
	ds_read_u16 v193, v185 offset:896
	ds_read_u16 v194, v185 offset:1024
	ds_read_u16 v196, v185 offset:1152
	ds_read_u16 v197, v185 offset:1280
	v_mul_u32_u24_e32 v206, 0x820, v183
	v_lshl_add_u32 v206, v184, 2, v206
	v_mul_u32_u24_e32 v207, 0x480, v183
	v_lshl_add_u32 v207, v184, 1, v207
	s_waitcnt lgkmcnt(0)
	v_lshlrev_b32_e32 v186, 16, v186
	v_lshlrev_b32_e32 v187, 16, v187
	v_lshlrev_b32_e32 v188, 16, v188
	v_lshlrev_b32_e32 v189, 16, v189
	v_lshlrev_b32_e32 v190, 16, v190
	v_lshlrev_b32_e32 v191, 16, v191
	v_lshlrev_b32_e32 v192, 16, v192
	v_lshlrev_b32_e32 v193, 16, v193
	v_lshlrev_b32_e32 v194, 16, v194
	v_lshlrev_b32_e32 v196, 16, v196
	v_lshlrev_b32_e32 v197, 16, v197
	v_fma_f32 v198, v151, v186, v150
	v_fma_f32 v199, v151, v187, v150
	v_fma_f32 v200, v151, v188, v150
	v_fma_f32 v201, v151, v189, v150
	v_fma_f32 v202, v151, v190, v150
	v_fma_f32 v203, v151, v191, v150
	v_fma_f32 v204, v151, v192, v150
	v_fma_f32 v205, v151, v193, v150
	v_fmac_f32_e32 v198, v154, v187
	v_fmac_f32_e32 v199, v154, v188
	v_fmac_f32_e32 v200, v154, v189
	v_fmac_f32_e32 v201, v154, v190
	v_fmac_f32_e32 v202, v154, v191
	v_fmac_f32_e32 v203, v154, v192
	v_fmac_f32_e32 v204, v154, v193
	v_fmac_f32_e32 v205, v154, v194
	v_fmac_f32_e32 v198, v153, v188
	v_fmac_f32_e32 v199, v153, v189
	v_fmac_f32_e32 v200, v153, v190
	v_fmac_f32_e32 v201, v153, v191
	v_fmac_f32_e32 v202, v153, v192
	v_fmac_f32_e32 v203, v153, v193
	v_fmac_f32_e32 v204, v153, v194
	v_fmac_f32_e32 v205, v153, v196
	v_fmac_f32_e32 v198, v152, v189
	v_fmac_f32_e32 v199, v152, v190
	v_fmac_f32_e32 v200, v152, v191
	v_fmac_f32_e32 v201, v152, v192
	v_fmac_f32_e32 v202, v152, v193
	v_fmac_f32_e32 v203, v152, v194
	v_fmac_f32_e32 v204, v152, v196
	v_fmac_f32_e32 v205, v152, v197
	ds_write_b32 v206, v198 offset:8704
	ds_write_b32 v206, v199 offset:8964
	ds_write_b32 v206, v200 offset:9224
	ds_write_b32 v206, v201 offset:9484
	ds_write_b32 v206, v202 offset:9744
	ds_write_b32 v206, v203 offset:10004
	ds_write_b32 v206, v204 offset:10264
	ds_write_b32 v206, v205 offset:10524
	v_cvt_pk_bf16_f32 v186, v198, v1
	v_cvt_pk_bf16_f32 v187, v199, v1
	ds_write_b16 v207, v186 offset:25344
	v_cvt_pk_bf16_f32 v188, v200, v1
	ds_write_b16 v207, v187 offset:25488
	v_cvt_pk_bf16_f32 v189, v201, v1
	ds_write_b16 v207, v188 offset:25632
	v_cvt_pk_bf16_f32 v190, v202, v1
	ds_write_b16 v207, v189 offset:25776
	v_cvt_pk_bf16_f32 v191, v203, v1
	ds_write_b16 v207, v190 offset:25920
	v_cvt_pk_bf16_f32 v192, v204, v1
	ds_write_b16 v207, v191 offset:26064
	v_cvt_pk_bf16_f32 v193, v205, v1
	ds_write_b16 v207, v192 offset:26208
	ds_write_b16 v207, v193 offset:26352
	s_waitcnt lgkmcnt(0)
	s_barrier
	ds_read_b128 v[18:21], v47 offset:25344
	ds_read_b128 v[14:17], v47 offset:25408
	ds_read_b128 v[160:163], v72 offset:34560
	ds_read_b128 v[164:167], v72 offset:34624
	s_waitcnt lgkmcnt(1)
	v_mfma_f32_16x16x32_bf16 v[160:163], v[18:21], v[160:163], 0
	ds_read_b128 v[168:171], v73 offset:43840
	s_waitcnt lgkmcnt(1)
	v_mfma_f32_16x16x32_bf16 v[160:163], v[14:17], v[164:167], v[160:163]
	ds_read_b128 v[164:167], v73 offset:43776
	s_waitcnt lgkmcnt(0)
	v_mfma_f32_16x16x32_bf16 v[164:167], v[18:21], v[164:167], 0
	s_waitcnt vmcnt(9)
	s_nop 3
	v_fmamk_f32 v0, v160, 0xbfb8aa3b, v157
	v_exp_f32_e32 v0, v0
	v_mfma_f32_16x16x32_bf16 v[164:167], v[14:17], v[168:171], v[164:167]
	v_add_f32_e32 v0, 1.0, v0
	v_rcp_f32_e32 v0, v0
	s_nop 0
	v_mul_f32_e32 v0, v23, v0
	v_exp_f32_e32 v0, v0
	s_waitcnt vmcnt(5)
	s_nop 1
	v_fmamk_f32 v35, v164, 0xbfb8aa3b, v155
	v_exp_f32_e32 v35, v35
	v_fma_f32 v36, -v0, v0, 1.0
	v_max_f32_e32 v36, 0, v36
	ds_write_b32 v74, v0
	v_add_f32_e32 v35, 1.0, v35
	v_sqrt_f32_e32 v37, v36
	v_rcp_f32_e32 v35, v35
	v_mov_b32_e32 v0, v37
	v_fmamk_f32 v37, v161, 0xbfb8aa3b, v157
	v_exp_f32_e32 v37, v37
	ds_read_b32 v159, v149 offset:8704
	v_add_f32_e32 v36, 1.0, v37
	v_rcp_f32_e32 v36, v36
	v_mul_f32_e32 v0, v35, v0
	s_waitcnt lgkmcnt(0)
	v_mul_f32_e32 v0, v159, v0
	ds_write_b32 v75, v0
	v_mul_f32_e32 v0, v23, v36
	v_exp_f32_e32 v0, v0
	v_fmamk_f32 v35, v165, 0xbfb8aa3b, v155
	v_exp_f32_e32 v35, v35
	v_fma_f32 v36, -v0, v0, 1.0
	v_max_f32_e32 v36, 0, v36
	ds_write_b32 v76, v0
	v_add_f32_e32 v35, 1.0, v35
	v_sqrt_f32_e32 v37, v36
	v_rcp_f32_e32 v35, v35
	v_mov_b32_e32 v0, v37
	v_fmamk_f32 v37, v162, 0xbfb8aa3b, v157
	v_exp_f32_e32 v37, v37
	ds_read_b32 v159, v149 offset:8964
	v_add_f32_e32 v36, 1.0, v37
	v_rcp_f32_e32 v36, v36
	v_mul_f32_e32 v0, v35, v0
	s_waitcnt lgkmcnt(0)
	v_mul_f32_e32 v0, v159, v0
	ds_write_b32 v77, v0
	v_mul_f32_e32 v0, v23, v36
	v_exp_f32_e32 v0, v0
	v_fmamk_f32 v35, v166, 0xbfb8aa3b, v155
	v_exp_f32_e32 v35, v35
	v_fma_f32 v36, -v0, v0, 1.0
	v_max_f32_e32 v36, 0, v36
	ds_write_b32 v78, v0
	v_add_f32_e32 v35, 1.0, v35
	v_sqrt_f32_e32 v37, v36
	v_rcp_f32_e32 v35, v35
	v_mov_b32_e32 v0, v37
	v_fmamk_f32 v37, v163, 0xbfb8aa3b, v157
	v_exp_f32_e32 v37, v37
	ds_read_b32 v159, v149 offset:9224
	v_add_f32_e32 v36, 1.0, v37
	v_rcp_f32_e32 v36, v36
	v_mul_f32_e32 v0, v35, v0
	s_waitcnt lgkmcnt(0)
	v_mul_f32_e32 v0, v159, v0
	ds_write_b32 v79, v0
	v_mul_f32_e32 v0, v23, v36
	v_exp_f32_e32 v0, v0
	v_fmamk_f32 v35, v167, 0xbfb8aa3b, v155
	v_exp_f32_e32 v35, v35
	v_fma_f32 v36, -v0, v0, 1.0
	v_max_f32_e32 v36, 0, v36
	ds_write_b32 v80, v0
	v_add_f32_e32 v35, 1.0, v35
	v_sqrt_f32_e32 v37, v36
	v_rcp_f32_e32 v35, v35
	v_mov_b32_e32 v0, v37
	ds_read_b32 v159, v149 offset:9484
	v_mul_f32_e32 v0, v35, v0
	s_waitcnt lgkmcnt(0)
; __device__ __forceinline__ float sigm(float x) { return __builtin_amdgcn_rcpf(1.0f + __expf(-x)); }
; template <int PASS>
; __device__ void lru_items(const Params& p, unsigned char* shm, int l) {
;     ...
;           for (int jt = 0; jt < 4; ++jt) {
;               f32x4 accr = (f32x4){0.f, 0.f, 0.f, 0.f}, acci = (f32x4){0.f, 0.f, 0.f, 0.f};
;               const bf16_t* wr_ = wt + ((d * 2 + 0) * 64 + jt * 16 + fr) * 72 + fq * 8; const bf16_t* wi_ = wt + ((d * 2 + 1) * 64 + jt * 16 + fr) * 72 + fq * 8;
;               accr = __builtin_amdgcn_mfma_f32_16x16x32_bf16(a0, *(const bf16x8*)wr_, accr, 0, 0, 0);
;               accr = __builtin_amdgcn_mfma_f32_16x16x32_bf16(a1, *(const bf16x8*)(wr_ + 32), accr, 0, 0, 0);
;               acci = __builtin_amdgcn_mfma_f32_16x16x32_bf16(a0, *(const bf16x8*)wi_, acci, 0, 0, 0);
;               acci = __builtin_amdgcn_mfma_f32_16x16x32_bf16(a1, *(const bf16x8*)(wi_ + 32), acci, 0, 0, 0);
;               const int j = jt * 16 + fr;
; #pragma unroll
;               for (int i = 0; i < 4; ++i) { const int t = tt * 16 + fq * 4 + i;
;                   const float r = sigm(accr[i] + gba[jt]), ig = sigm(acci[i] + gbx[jt]), a = __expf(r * gsp[jt]);
;                   As[(d * 64 + t) * 64 + j] = a;
;                   Bs[(d * 64 + t) * 64 + j] = sqrtf(fmaxf(1.0f - a * a, 0.f)) * ig * xcf[t * 65 + j]; }
	v_mul_f32_e32 v0, v0, v159
	ds_write_b32 v81, v0
	ds_read_b128 v[160:163], v72 offset:36864
	ds_read_b128 v[164:167], v72 offset:36928
	s_waitcnt lgkmcnt(1)
	v_mfma_f32_16x16x32_bf16 v[160:163], v[18:21], v[160:163], 0
	ds_read_b128 v[168:171], v73 offset:46144
	s_waitcnt lgkmcnt(1)
	v_mfma_f32_16x16x32_bf16 v[160:163], v[14:17], v[164:167], v[160:163]
	ds_read_b128 v[164:167], v73 offset:46080
	s_waitcnt lgkmcnt(0)
	v_mfma_f32_16x16x32_bf16 v[164:167], v[18:21], v[164:167], 0
	s_nop 4
	v_fmamk_f32 v0, v160, 0xbfb8aa3b, v158
	v_exp_f32_e32 v0, v0
	v_mfma_f32_16x16x32_bf16 v[164:167], v[14:17], v[168:171], v[164:167]
	v_add_f32_e32 v0, 1.0, v0
	v_rcp_f32_e32 v0, v0
	s_nop 0
	v_mul_f32_e32 v0, v22, v0
	v_exp_f32_e32 v0, v0
	s_waitcnt vmcnt(4)
	s_nop 1
	v_fmamk_f32 v35, v164, 0xbfb8aa3b, v156
	v_exp_f32_e32 v35, v35
	v_fma_f32 v36, -v0, v0, 1.0
	v_max_f32_e32 v36, 0, v36
	ds_write_b32 v82, v0
	v_add_f32_e32 v35, 1.0, v35
	v_sqrt_f32_e32 v37, v36
	v_rcp_f32_e32 v35, v35
	v_mov_b32_e32 v0, v37
	v_fmamk_f32 v37, v161, 0xbfb8aa3b, v158
	v_exp_f32_e32 v37, v37
	ds_read_b32 v159, v149 offset:8768
	v_add_f32_e32 v36, 1.0, v37
	v_rcp_f32_e32 v36, v36
	v_mul_f32_e32 v0, v35, v0
	s_waitcnt lgkmcnt(0)
	v_mul_f32_e32 v0, v159, v0
	ds_write_b32 v83, v0
	v_mul_f32_e32 v0, v22, v36
	v_exp_f32_e32 v0, v0
	v_fmamk_f32 v35, v165, 0xbfb8aa3b, v156
	v_exp_f32_e32 v35, v35
	v_fma_f32 v36, -v0, v0, 1.0
	v_max_f32_e32 v36, 0, v36
	ds_write_b32 v84, v0
	v_add_f32_e32 v35, 1.0, v35
	v_sqrt_f32_e32 v37, v36
	v_rcp_f32_e32 v35, v35
	v_mov_b32_e32 v0, v37
	v_fmamk_f32 v37, v162, 0xbfb8aa3b, v158
	v_exp_f32_e32 v37, v37
	ds_read_b32 v159, v149 offset:9028
	v_add_f32_e32 v36, 1.0, v37
	v_rcp_f32_e32 v36, v36
	v_mul_f32_e32 v0, v35, v0
	s_waitcnt lgkmcnt(0)
	v_mul_f32_e32 v0, v159, v0
	ds_write_b32 v85, v0
	v_mul_f32_e32 v0, v22, v36
	v_exp_f32_e32 v0, v0
	v_fmamk_f32 v35, v166, 0xbfb8aa3b, v156
	v_exp_f32_e32 v35, v35
	v_fma_f32 v36, -v0, v0, 1.0
	v_max_f32_e32 v36, 0, v36
	ds_write_b32 v86, v0
	v_add_f32_e32 v35, 1.0, v35
	v_sqrt_f32_e32 v37, v36
	v_rcp_f32_e32 v35, v35
	v_mov_b32_e32 v0, v37
	v_fmamk_f32 v37, v163, 0xbfb8aa3b, v158
	v_exp_f32_e32 v37, v37
	ds_read_b32 v159, v149 offset:9288
	v_add_f32_e32 v36, 1.0, v37
	v_rcp_f32_e32 v36, v36
	v_mul_f32_e32 v0, v35, v0
	s_waitcnt lgkmcnt(0)
	v_mul_f32_e32 v0, v159, v0
	ds_write_b32 v87, v0
	v_mul_f32_e32 v0, v22, v36
	v_exp_f32_e32 v0, v0
	v_fmamk_f32 v35, v167, 0xbfb8aa3b, v156
	v_exp_f32_e32 v35, v35
	v_fma_f32 v36, -v0, v0, 1.0
	v_max_f32_e32 v36, 0, v36
	ds_write_b32 v88, v0
	v_add_f32_e32 v35, 1.0, v35
	v_sqrt_f32_e32 v37, v36
	v_rcp_f32_e32 v35, v35
	v_mov_b32_e32 v0, v37
	ds_read_b32 v159, v149 offset:9548
	v_mul_f32_e32 v0, v35, v0
	s_waitcnt lgkmcnt(0)
	v_mul_f32_e32 v0, v0, v159
	ds_write_b32 v89, v0
	ds_read_b128 v[160:163], v72 offset:39168
	ds_read_b128 v[164:167], v72 offset:39232
	s_waitcnt lgkmcnt(1)
	v_mfma_f32_16x16x32_bf16 v[160:163], v[18:21], v[160:163], 0
	ds_read_b128 v[168:171], v73 offset:48448
	s_waitcnt lgkmcnt(1)
	v_mfma_f32_16x16x32_bf16 v[160:163], v[14:17], v[164:167], v[160:163]
	ds_read_b128 v[164:167], v73 offset:48384
	s_waitcnt lgkmcnt(0)
	v_mfma_f32_16x16x32_bf16 v[164:167], v[18:21], v[164:167], 0
	s_nop 4
	v_fmamk_f32 v0, v160, 0xbfb8aa3b, v40
	v_exp_f32_e32 v0, v0
	v_mfma_f32_16x16x32_bf16 v[164:167], v[14:17], v[168:171], v[164:167]
	v_add_f32_e32 v0, 1.0, v0
	v_rcp_f32_e32 v0, v0
	s_nop 0
	v_mul_f32_e32 v0, v25, v0
	v_exp_f32_e32 v0, v0
	s_waitcnt vmcnt(3)
	s_nop 1
	v_fmamk_f32 v35, v164, 0xbfb8aa3b, v38
	v_exp_f32_e32 v35, v35
	v_fma_f32 v36, -v0, v0, 1.0
	v_max_f32_e32 v36, 0, v36
	ds_write_b32 v90, v0
	v_add_f32_e32 v35, 1.0, v35
	v_sqrt_f32_e32 v37, v36
	v_rcp_f32_e32 v35, v35
	v_mov_b32_e32 v0, v37
	v_fmamk_f32 v37, v161, 0xbfb8aa3b, v40
	v_exp_f32_e32 v37, v37
	ds_read_b32 v159, v149 offset:8832
	v_add_f32_e32 v36, 1.0, v37
	v_rcp_f32_e32 v36, v36
	v_mul_f32_e32 v0, v35, v0
	s_waitcnt lgkmcnt(0)
	v_mul_f32_e32 v0, v159, v0
	ds_write_b32 v91, v0
	v_mul_f32_e32 v0, v25, v36
	v_exp_f32_e32 v0, v0
	v_fmamk_f32 v35, v165, 0xbfb8aa3b, v38
	v_exp_f32_e32 v35, v35
	v_fma_f32 v36, -v0, v0, 1.0
	v_max_f32_e32 v36, 0, v36
	ds_write_b32 v92, v0
	v_add_f32_e32 v35, 1.0, v35
	v_sqrt_f32_e32 v37, v36
	v_rcp_f32_e32 v35, v35
	v_mov_b32_e32 v0, v37
	v_fmamk_f32 v37, v162, 0xbfb8aa3b, v40
	v_exp_f32_e32 v37, v37
	ds_read_b32 v159, v149 offset:9092
	v_add_f32_e32 v36, 1.0, v37
	v_rcp_f32_e32 v36, v36
	v_mul_f32_e32 v0, v35, v0
	s_waitcnt lgkmcnt(0)
	v_mul_f32_e32 v0, v159, v0
	ds_write_b32 v93, v0
	v_mul_f32_e32 v0, v25, v36
	v_exp_f32_e32 v0, v0
	v_fmamk_f32 v35, v166, 0xbfb8aa3b, v38
	v_exp_f32_e32 v35, v35
	v_fma_f32 v36, -v0, v0, 1.0
	v_max_f32_e32 v36, 0, v36
	ds_write_b32 v94, v0
	v_add_f32_e32 v35, 1.0, v35
	v_sqrt_f32_e32 v37, v36
	v_rcp_f32_e32 v35, v35
	v_mov_b32_e32 v0, v37
	v_fmamk_f32 v37, v163, 0xbfb8aa3b, v40
	v_exp_f32_e32 v37, v37
	ds_read_b32 v159, v149 offset:9352
	v_add_f32_e32 v36, 1.0, v37
	v_rcp_f32_e32 v36, v36
	v_mul_f32_e32 v0, v35, v0
	s_waitcnt lgkmcnt(0)
	v_mul_f32_e32 v0, v159, v0
	ds_write_b32 v95, v0
	v_mul_f32_e32 v0, v25, v36
	v_exp_f32_e32 v0, v0
	v_fmamk_f32 v35, v167, 0xbfb8aa3b, v38
	v_exp_f32_e32 v35, v35
	v_fma_f32 v36, -v0, v0, 1.0
	v_max_f32_e32 v36, 0, v36
	ds_write_b32 v96, v0
	v_add_f32_e32 v35, 1.0, v35
	v_sqrt_f32_e32 v37, v36
	v_rcp_f32_e32 v35, v35
	v_mov_b32_e32 v0, v37
	ds_read_b32 v159, v149 offset:9612
	v_mul_f32_e32 v0, v35, v0
	s_waitcnt lgkmcnt(0)
; __device__ __forceinline__ float sigm(float x) { return __builtin_amdgcn_rcpf(1.0f + __expf(-x)); }
; template <int PASS>
; __device__ void lru_items(const Params& p, unsigned char* shm, int l) {
;     ...
;           for (int jt = 0; jt < 4; ++jt) {
;               f32x4 accr = (f32x4){0.f, 0.f, 0.f, 0.f}, acci = (f32x4){0.f, 0.f, 0.f, 0.f};
;               const bf16_t* wr_ = wt + ((d * 2 + 0) * 64 + jt * 16 + fr) * 72 + fq * 8; const bf16_t* wi_ = wt + ((d * 2 + 1) * 64 + jt * 16 + fr) * 72 + fq * 8;
;               accr = __builtin_amdgcn_mfma_f32_16x16x32_bf16(a0, *(const bf16x8*)wr_, accr, 0, 0, 0);
;               accr = __builtin_amdgcn_mfma_f32_16x16x32_bf16(a1, *(const bf16x8*)(wr_ + 32), accr, 0, 0, 0);
;               acci = __builtin_amdgcn_mfma_f32_16x16x32_bf16(a0, *(const bf16x8*)wi_, acci, 0, 0, 0);
;               acci = __builtin_amdgcn_mfma_f32_16x16x32_bf16(a1, *(const bf16x8*)(wi_ + 32), acci, 0, 0, 0);
;               const int j = jt * 16 + fr;
; #pragma unroll
;               for (int i = 0; i < 4; ++i) { const int t = tt * 16 + fq * 4 + i;
;                   const float r = sigm(accr[i] + gba[jt]), ig = sigm(acci[i] + gbx[jt]), a = __expf(r * gsp[jt]);
;                   As[(d * 64 + t) * 64 + j] = a;
;                   Bs[(d * 64 + t) * 64 + j] = sqrtf(fmaxf(1.0f - a * a, 0.f)) * ig * xcf[t * 65 + j]; }
;           } }
;         __syncthreads();
;         {
;             const int seg = tid >> 7, d = (tid >> 6) & 1, j = tid & 63;
;             float h = 0.f, P = 1.f;
; #pragma unroll
;             for (int s = 0; s < 16; ++s) { const int st = seg * 16 + s, t = d ? 63 - st : st; const float a = As[(d * 64 + t) * 64 + j]; h = a * h + Bs[(d * 64 + t) * 64 + j]; P *= a; }
;             Pq[seg * 128 + (tid & 127)] = P; Hq[seg * 128 + (tid & 127)] = h;
;             __syncthreads();
	v_mul_f32_e32 v0, v0, v159
	ds_write_b32 v97, v0
	ds_read_b128 v[160:163], v72 offset:41472
	ds_read_b128 v[164:167], v72 offset:41536
	s_waitcnt lgkmcnt(1)
	v_mfma_f32_16x16x32_bf16 v[160:163], v[18:21], v[160:163], 0
	ds_read_b128 v[168:171], v73 offset:50752
	s_waitcnt lgkmcnt(1)
	v_mfma_f32_16x16x32_bf16 v[160:163], v[14:17], v[164:167], v[160:163]
	ds_read_b128 v[164:167], v73 offset:50688
	s_waitcnt lgkmcnt(0)
	v_mfma_f32_16x16x32_bf16 v[18:21], v[18:21], v[164:167], 0
	s_nop 4
	v_fmamk_f32 v0, v160, 0xbfb8aa3b, v41
	v_exp_f32_e32 v0, v0
	s_nop 0
	v_mfma_f32_16x16x32_bf16 v[14:17], v[14:17], v[168:171], v[18:21]
	v_add_f32_e32 v0, 1.0, v0
	v_rcp_f32_e32 v0, v0
	s_nop 0
	v_mul_f32_e32 v0, v24, v0
	v_exp_f32_e32 v0, v0
	s_waitcnt vmcnt(2)
	s_nop 1
	v_fmamk_f32 v14, v14, 0xbfb8aa3b, v39
	v_exp_f32_e32 v14, v14
	v_fma_f32 v18, -v0, v0, 1.0
	v_max_f32_e32 v18, 0, v18
	ds_write_b32 v98, v0
	v_add_f32_e32 v14, 1.0, v14
	v_sqrt_f32_e32 v19, v18
	v_rcp_f32_e32 v14, v14
	v_mov_b32_e32 v0, v19
	v_fmamk_f32 v19, v161, 0xbfb8aa3b, v41
	v_exp_f32_e32 v19, v19
	ds_read_b32 v20, v149 offset:8896
	v_add_f32_e32 v18, 1.0, v19
	v_rcp_f32_e32 v18, v18
	v_mul_f32_e32 v0, v14, v0
	s_waitcnt lgkmcnt(0)
	v_mul_f32_e32 v0, v20, v0
	ds_write_b32 v99, v0
	v_mul_f32_e32 v0, v24, v18
	v_exp_f32_e32 v0, v0
	v_fmamk_f32 v14, v15, 0xbfb8aa3b, v39
	v_exp_f32_e32 v14, v14
	v_fma_f32 v15, -v0, v0, 1.0
	v_max_f32_e32 v15, 0, v15
	ds_write_b32 v100, v0
	v_add_f32_e32 v14, 1.0, v14
	v_sqrt_f32_e32 v18, v15
	v_rcp_f32_e32 v14, v14
	v_mov_b32_e32 v0, v18
	v_fmamk_f32 v18, v162, 0xbfb8aa3b, v41
	v_exp_f32_e32 v18, v18
	ds_read_b32 v19, v149 offset:9156
	v_add_f32_e32 v15, 1.0, v18
	v_rcp_f32_e32 v15, v15
	v_mul_f32_e32 v0, v14, v0
	s_waitcnt lgkmcnt(0)
	v_mul_f32_e32 v0, v19, v0
	ds_write_b32 v101, v0
	v_mul_f32_e32 v0, v24, v15
	v_exp_f32_e32 v0, v0
	v_fmamk_f32 v14, v16, 0xbfb8aa3b, v39
	v_exp_f32_e32 v14, v14
	v_fma_f32 v15, -v0, v0, 1.0
	v_max_f32_e32 v15, 0, v15
	ds_write_b32 v102, v0
	v_add_f32_e32 v14, 1.0, v14
	v_sqrt_f32_e32 v16, v15
	v_rcp_f32_e32 v14, v14
	v_mov_b32_e32 v0, v16
	v_fmamk_f32 v16, v163, 0xbfb8aa3b, v41
	v_exp_f32_e32 v16, v16
	ds_read_b32 v18, v149 offset:9416
	v_add_f32_e32 v15, 1.0, v16
	v_rcp_f32_e32 v15, v15
	v_mul_f32_e32 v0, v14, v0
	s_waitcnt lgkmcnt(0)
	v_mul_f32_e32 v0, v18, v0
	ds_write_b32 v103, v0
	v_mul_f32_e32 v0, v24, v15
	v_exp_f32_e32 v0, v0
	v_fmamk_f32 v14, v17, 0xbfb8aa3b, v39
	v_exp_f32_e32 v14, v14
	v_fma_f32 v15, -v0, v0, 1.0
	v_max_f32_e32 v15, 0, v15
	ds_write_b32 v104, v0
	v_add_f32_e32 v14, 1.0, v14
	v_sqrt_f32_e32 v16, v15
	v_rcp_f32_e32 v14, v14
	v_mov_b32_e32 v0, v16
	ds_read_b32 v17, v149 offset:9676
	v_mul_f32_e32 v0, v14, v0
	s_waitcnt lgkmcnt(0)
	v_mul_f32_e32 v0, v0, v17
	ds_write_b32 v105, v0
	s_waitcnt lgkmcnt(0)
	s_barrier
	ds_read_b32 v0, v51
	ds_read_b32 v14, v106
	ds_read_b32 v15, v107
	ds_read_b32 v16, v108
	ds_read_b32 v17, v109
	ds_read_b32 v18, v110
	ds_read_b32 v19, v111
	ds_read_b32 v20, v112
	s_waitcnt lgkmcnt(6)
	v_fmac_f32_e32 v14, 0, v0
	s_waitcnt lgkmcnt(4)
	v_fmac_f32_e32 v16, v14, v15
	v_mul_f32_e32 v0, v0, v15
	s_waitcnt lgkmcnt(2)
	v_fmac_f32_e32 v18, v16, v17
	v_mul_f32_e32 v0, v0, v17
	s_waitcnt lgkmcnt(0)
	v_fmac_f32_e32 v20, v18, v19
	v_mul_f32_e32 v0, v0, v19
	ds_read_b32 v14, v113
	ds_read_b32 v15, v114
	ds_read_b32 v16, v115
	ds_read_b32 v17, v116
	ds_read_b32 v18, v117
	ds_read_b32 v19, v118
	ds_read_b32 v21, v119
	ds_read_b32 v35, v120
	s_waitcnt lgkmcnt(6)
	v_fmac_f32_e32 v15, v20, v14
	v_mul_f32_e32 v0, v0, v14
	s_waitcnt lgkmcnt(4)
	v_fmac_f32_e32 v17, v15, v16
	v_mul_f32_e32 v0, v0, v16
	s_waitcnt lgkmcnt(2)
	v_fmac_f32_e32 v19, v17, v18
	v_mul_f32_e32 v0, v0, v18
	s_waitcnt lgkmcnt(0)
	v_fmac_f32_e32 v35, v19, v21
	v_mul_f32_e32 v0, v0, v21
	ds_read_b32 v14, v121
	ds_read_b32 v15, v122
	ds_read_b32 v16, v123
	ds_read_b32 v17, v124
	ds_read_b32 v18, v125
	ds_read_b32 v19, v126
	ds_read_b32 v20, v127
	ds_read_b32 v21, v128
	s_waitcnt lgkmcnt(6)
	v_fmac_f32_e32 v15, v35, v14
	v_mul_f32_e32 v0, v0, v14
	s_waitcnt lgkmcnt(4)
	v_fmac_f32_e32 v17, v15, v16
	v_mul_f32_e32 v0, v0, v16
	s_waitcnt lgkmcnt(2)
	v_fmac_f32_e32 v19, v17, v18
	v_mul_f32_e32 v0, v0, v18
	s_waitcnt lgkmcnt(0)
	v_fmac_f32_e32 v21, v19, v20
	v_mul_f32_e32 v0, v0, v20
	ds_read_b32 v14, v129
	ds_read_b32 v15, v130
	ds_read_b32 v16, v131
	ds_read_b32 v17, v132
	ds_read_b32 v18, v133
	ds_read_b32 v19, v134
	ds_read_b32 v20, v135
	ds_read_b32 v35, v136
	s_waitcnt lgkmcnt(7)
	v_mul_f32_e32 v0, v0, v14
	s_waitcnt lgkmcnt(6)
	v_fmac_f32_e32 v15, v21, v14
	s_waitcnt lgkmcnt(5)
	v_mul_f32_e32 v0, v0, v16
	s_waitcnt lgkmcnt(4)
	v_fmac_f32_e32 v17, v15, v16
	s_waitcnt lgkmcnt(3)
	v_mul_f32_e32 v0, v0, v18
	s_waitcnt lgkmcnt(2)
	v_fmac_f32_e32 v19, v17, v18
	s_waitcnt lgkmcnt(1)
	v_mul_f32_e32 v0, v0, v20
	s_waitcnt lgkmcnt(0)
	v_fmac_f32_e32 v35, v19, v20
	ds_write_b32 v48, v0
	ds_write_b32 v49, v35
	s_waitcnt lgkmcnt(0)
	s_barrier
	s_and_saveexec_b64 s[0:1], s[38:39]
	s_cbranch_execnz .LBB0_217
	s_or_b64 exec, exec, s[0:1]
	s_and_saveexec_b64 s[0:1], s[40:41]
	s_cbranch_execnz .LBB0_218

; template <int PASS>
; __device__ void lru_items(const Params& p, unsigned char* shm, int l) {
;     ...
;         *(u32x4*)(xraw + (tid >> 3) * 64 + (tid & 7) * 8) = xr0;
;         if (tid < 24) *(u32x4*)(xraw + (64 + (tid >> 3)) * 64 + (tid & 7) * 8) = xr1;
;         if (n != n_loaded) {
;             n_loaded = n;
; #pragma unroll
;             for (int i = 0; i < 4; ++i) { const int e = tid + 512 * i, mtx = e >> 9, rem = e & 511, j = rem >> 3, c8 = rem & 7;
;                 *(u32x4*)(wt + (mtx * 64 + j) * 72 + c8 * 8) = *(const u32x4*)(LWT + ((size_t)(mtx * 16 + n) * 64 + j) * 64 + c8 * 8); }
;             { const int ch = n * 64 + (tid & 63); c0 = cw[ch]; c1 = cw[1024 + ch]; c2 = cw[2048 + ch]; c3 = cw[3072 + ch]; cb = cbias[ch]; }
; #pragma unroll
;             for (int jt = 0; jt < 4; ++jt) { const int pi = (l * 2 + (w >> 2)) * 1024 + n * 64 + jt * 16 + fr; gba[jt] = p.in[7][pi]; gbx[jt] = p.in[9][pi]; gsp[jt] = -8.0f * log1pf(__expf(-p.in[10][pi])); }
.LBB0_296:
	s_waitcnt vmcnt(0)
	ds_write_b128 v29, v[2:5]
	s_and_saveexec_b64 s[0:1], s[36:37]
	ds_write_b128 v29, v[6:9] offset:8192
	s_or_b64 exec, exec, s[0:1]
	s_and_b32 s4, s2, 15
	s_cmp_lg_u32 s4, s6
	s_mov_b64 s[0:1], -1
	s_cbranch_scc0 .LBB0_300
	v_or_b32_e32 v10, s4, v47
	v_or_b32_e32 v12, s4, v48
	s_lshl_b32 s50, s4, 6
	v_ashrrev_i32_e32 v11, 31, v10
	v_ashrrev_i32_e32 v13, 31, v12
	v_or_b32_e32 v22, s50, v42
	v_lshlrev_b64 v[10:11], 13, v[10:11]
	v_lshlrev_b64 v[12:13], 13, v[12:13]
	v_ashrrev_i32_e32 v23, 31, v22
	v_readlane_b32 s76, v251, 36
	v_lshl_add_u64 v[10:11], v[30:31], 0, v[10:11]
	v_lshl_add_u64 v[14:15], v[30:31], 0, v[12:13]
	v_lshlrev_b64 v[36:37], 2, v[22:23]
	v_readlane_b32 s80, v251, 40
	v_readlane_b32 s81, v251, 41
	global_load_dwordx4 v[10:13], v[10:11], off
	s_nop 0
	global_load_dwordx4 v[14:17], v[14:15], off
	v_lshl_add_u64 v[40:41], s[80:81], 0, v[36:37]
	global_load_dword v168, v[40:41], off
	global_load_dword v169, v[40:41], off offset:64
	v_or_b32_e32 v18, s4, v49
	v_or_b32_e32 v20, s4, v50
	v_ashrrev_i32_e32 v19, 31, v18
	v_ashrrev_i32_e32 v21, 31, v20
	v_lshlrev_b64 v[18:19], 13, v[18:19]
	v_lshlrev_b64 v[20:21], 13, v[20:21]
	v_lshl_add_u64 v[18:19], v[30:31], 0, v[18:19]
	v_lshl_add_u64 v[22:23], v[30:31], 0, v[20:21]
	global_load_dwordx4 v[18:21], v[18:19], off
	s_nop 0
	global_load_dwordx4 v[22:25], v[22:23], off
	v_or_b32_e32 v0, s50, v26
	v_lshlrev_b32_e32 v0, 2, v0
	v_lshl_add_u64 v[38:39], s[42:43], 0, v[0:1]
	s_movk_i32 s0, 0x2000
	v_add_co_u32_e32 v150, vcc, s0, v38
	s_movk_i32 s0, 0x3000
	s_nop 0
	v_addc_co_u32_e32 v151, vcc, 0, v39, vcc
	v_add_co_u32_e32 v166, vcc, s0, v38
	global_load_dword v149, v0, s[42:43]
	global_load_dword v148, v0, s[46:47]
	v_addc_co_u32_e32 v167, vcc, 0, v39, vcc
	global_load_dword v152, v[150:151], off offset:-4096
	s_nop 0
	global_load_dword v151, v[150:151], off
	s_nop 0
	global_load_dword v150, v[166:167], off
	global_load_dword v0, v[40:41], off offset:128
	global_load_dword v176, v[40:41], off offset:192
	s_mov_b32 s0, 0x3f2aaaab
	s_mov_b32 s8, 0x3ecc95a3
	s_mov_b32 s18, 0x3f2aaada
	s_mov_b32 s28, 0x3f317218
	s_mov_b32 s40, 0xb102e308
	s_mov_b32 s1, 0x7f800000
	s_mov_b32 s5, 0x33800000
	s_mov_b32 s48, 0xc1000000
	v_readlane_b32 s60, v251, 20
	v_readlane_b32 s78, v251, 38
	v_readlane_b32 s79, v251, 39
	v_readlane_b32 s74, v251, 34
	v_readlane_b32 s75, v251, 35
	v_readlane_b32 s88, v251, 48
	v_readlane_b32 s89, v251, 49
	v_lshl_add_u64 v[38:39], s[74:75], 0, v[36:37]
	v_lshl_add_u64 v[36:37], s[78:79], 0, v[36:37]
	v_readlane_b32 s90, v251, 50
	v_readlane_b32 s91, v251, 51
	v_readlane_b32 s82, v251, 42
	v_readlane_b32 s84, v251, 44
	v_readlane_b32 s88, v254, 27
	v_readlane_b32 s90, v254, 25
	v_readlane_b32 s77, v251, 37
	v_readlane_b32 s83, v251, 43
	v_readlane_b32 s85, v251, 45
	v_readlane_b32 s86, v251, 46
	v_readlane_b32 s87, v251, 47
	v_readlane_b32 s92, v254, 21
	v_readlane_b32 s84, v254, 58
	s_movk_i32 s82, 0x60
	v_readlane_b32 s89, v254, 28
	v_readlane_b32 s91, v254, 26
	v_readlane_b32 s80, v254, 20
	v_readlane_b32 s61, v251, 21
	v_readlane_b32 s62, v251, 22
	v_readlane_b32 s63, v251, 23
	v_readlane_b32 s64, v251, 24
	v_readlane_b32 s65, v251, 25
	v_readlane_b32 s66, v251, 26
	v_readlane_b32 s67, v251, 27
	v_readlane_b32 s68, v251, 28
	s_waitcnt vmcnt(12)
	ds_write_b128 v141, v[10:13] offset:34560
	s_waitcnt vmcnt(11)
	ds_write_b128 v142, v[14:17] offset:34560
	s_waitcnt vmcnt(10)
	v_mul_f32_e32 v10, 0xbfb8aa3b, v168
	v_exp_f32_e32 v177, v10
	s_waitcnt vmcnt(9)
	v_mul_f32_e32 v11, 0xbfb8aa3b, v169
	v_exp_f32_e32 v178, v11
	s_waitcnt vmcnt(8)
	ds_write_b128 v143, v[18:21] offset:34560
	s_waitcnt vmcnt(7)
	ds_write_b128 v144, v[22:25] offset:34560
	v_add_f32_e32 v14, 1.0, v177
	v_frexp_mant_f32_e32 v17, v14
	v_cvt_f64_f32_e32 v[10:11], v14
	v_add_f32_e32 v15, 1.0, v178
	v_frexp_exp_i32_f64_e32 v10, v[10:11]
	v_cmp_gt_f32_e32 vcc, s0, v17
	v_add_f32_e32 v16, -1.0, v14
	v_frexp_mant_f32_e32 v19, v15
	v_cvt_f64_f32_e32 v[12:13], v15
	v_subbrev_co_u32_e32 v168, vcc, 0, v10, vcc
	v_add_f32_e32 v18, -1.0, v15
	v_sub_f32_e32 v20, v16, v14
	v_frexp_exp_i32_f64_e32 v12, v[12:13]
	v_cmp_gt_f32_e32 vcc, s0, v19
	v_sub_f32_e32 v16, v177, v16
	v_sub_f32_e32 v11, v18, v15
	v_add_f32_e32 v13, 1.0, v20
	v_subbrev_co_u32_e32 v169, vcc, 0, v12, vcc
	v_sub_f32_e32 v18, v178, v18
	v_add_f32_e32 v10, 1.0, v11
	v_add_f32_e32 v12, v16, v13
	v_sub_u32_e32 v13, 0, v168
	v_sub_u32_e32 v17, 0, v169
	v_add_f32_e32 v16, v18, v10
	v_ldexp_f32 v11, v14, v13
	v_ldexp_f32 v10, v15, v17
	v_pk_add_f32 v[14:15], v[10:11], 1.0 op_sel_hi:[1,0]
	v_ldexp_f32 v13, v12, v13
	v_ldexp_f32 v12, v16, v17
	v_pk_add_f32 v[16:17], v[10:11], -1.0 op_sel_hi:[1,0]
	v_pk_add_f32 v[18:19], v[14:15], -1.0 op_sel_hi:[1,0]
	v_pk_add_f32 v[20:21], v[16:17], 1.0 op_sel_hi:[1,0]
	v_pk_add_f32 v[18:19], v[10:11], v[18:19] neg_lo:[0,1] neg_hi:[0,1]
	v_pk_add_f32 v[10:11], v[10:11], v[20:21] neg_lo:[0,1] neg_hi:[0,1]
	v_pk_add_f32 v[18:19], v[12:13], v[18:19]
	v_pk_add_f32 v[10:11], v[12:13], v[10:11]
	v_pk_add_f32 v[12:13], v[14:15], v[18:19]
	v_pk_add_f32 v[20:21], v[16:17], v[10:11]
	v_rcp_f32_e32 v23, v13
	v_rcp_f32_e32 v22, v12
	v_pk_add_f32 v[16:17], v[20:21], v[16:17] neg_lo:[0,1] neg_hi:[0,1]
	v_pk_add_f32 v[14:15], v[12:13], v[14:15] neg_lo:[0,1] neg_hi:[0,1]
	v_pk_add_f32 v[10:11], v[10:11], v[16:17] neg_lo:[0,1] neg_hi:[0,1]
	v_pk_mul_f32 v[16:17], v[20:21], v[22:23]
	v_pk_add_f32 v[14:15], v[18:19], v[14:15] neg_lo:[0,1] neg_hi:[0,1]
	v_pk_mul_f32 v[18:19], v[12:13], v[16:17]
	v_cmp_neq_f32_e32 vcc, s1, v178
	v_pk_fma_f32 v[24:25], v[16:17], v[12:13], v[18:19] neg_lo:[0,0,1] neg_hi:[0,0,1]
	s_waitcnt vmcnt(1)
; template <int PASS>
; __device__ void lru_items(const Params& p, unsigned char* shm, int l) {
;     ...
;             { const int ch = n * 64 + (tid & 63); c0 = cw[ch]; c1 = cw[1024 + ch]; c2 = cw[2048 + ch]; c3 = cw[3072 + ch]; cb = cbias[ch]; }
; #pragma unroll
;             for (int jt = 0; jt < 4; ++jt) { const int pi = (l * 2 + (w >> 2)) * 1024 + n * 64 + jt * 16 + fr; gba[jt] = p.in[7][pi]; gbx[jt] = p.in[9][pi]; gsp[jt] = -8.0f * log1pf(__expf(-p.in[10][pi])); }
	v_mul_f32_e32 v0, 0xbfb8aa3b, v0
	v_pk_fma_f32 v[24:25], v[16:17], v[14:15], v[24:25]
	v_exp_f32_e32 v0, v0
	v_pk_add_f32 v[40:41], v[18:19], v[24:25]
	v_readlane_b32 s69, v251, 29
	v_pk_add_f32 v[166:167], v[20:21], v[40:41] neg_lo:[0,1] neg_hi:[0,1]
	v_pk_add_f32 v[18:19], v[40:41], v[18:19] neg_lo:[0,1] neg_hi:[0,1]
	v_pk_add_f32 v[20:21], v[20:21], v[166:167] neg_lo:[0,1] neg_hi:[0,1]
	v_pk_add_f32 v[18:19], v[18:19], v[24:25] neg_lo:[0,1] neg_hi:[0,1]
	v_pk_add_f32 v[20:21], v[20:21], v[40:41] neg_lo:[0,1] neg_hi:[0,1]
	v_readlane_b32 s70, v251, 30
	v_pk_add_f32 v[10:11], v[10:11], v[20:21]
	v_readlane_b32 s71, v251, 31
	v_pk_add_f32 v[10:11], v[18:19], v[10:11]
	v_readlane_b32 s72, v251, 32
	v_pk_add_f32 v[18:19], v[166:167], v[10:11]
	v_readlane_b32 s73, v251, 33
	v_pk_mul_f32 v[20:21], v[22:23], v[18:19]
	v_pk_add_f32 v[24:25], v[166:167], v[18:19] neg_lo:[0,1] neg_hi:[0,1]
	v_pk_mul_f32 v[40:41], v[12:13], v[20:21]
	v_pk_add_f32 v[10:11], v[10:11], v[24:25]
	v_pk_fma_f32 v[12:13], v[20:21], v[12:13], v[40:41] neg_lo:[0,0,1] neg_hi:[0,0,1]
	s_nop 0
	v_pk_fma_f32 v[12:13], v[20:21], v[14:15], v[12:13]
	s_nop 0
	v_pk_add_f32 v[14:15], v[40:41], v[12:13]
	s_nop 0
	v_pk_add_f32 v[24:25], v[14:15], v[40:41] neg_lo:[0,1] neg_hi:[0,1]
	v_pk_add_f32 v[40:41], v[18:19], v[14:15] neg_lo:[0,1] neg_hi:[0,1]
	v_pk_add_f32 v[12:13], v[24:25], v[12:13] neg_lo:[0,1] neg_hi:[0,1]
	v_pk_add_f32 v[18:19], v[18:19], v[40:41] neg_lo:[0,1] neg_hi:[0,1]
	s_nop 0
	v_pk_add_f32 v[14:15], v[18:19], v[14:15] neg_lo:[0,1] neg_hi:[0,1]
	s_nop 0
	v_pk_add_f32 v[10:11], v[10:11], v[14:15]
	s_nop 0
	v_pk_add_f32 v[10:11], v[12:13], v[10:11]
	v_pk_add_f32 v[12:13], v[16:17], v[20:21]
	v_pk_add_f32 v[10:11], v[40:41], v[10:11]
	v_pk_add_f32 v[14:15], v[12:13], v[16:17] neg_lo:[0,1] neg_hi:[0,1]
	v_pk_mul_f32 v[10:11], v[22:23], v[10:11]
	v_pk_add_f32 v[14:15], v[20:21], v[14:15] neg_lo:[0,1] neg_hi:[0,1]
	v_mov_b64_e32 v[20:21], s[8:9]
	v_pk_add_f32 v[10:11], v[14:15], v[10:11]
	s_mov_b32 s8, 0x3e9b6dac
	v_pk_add_f32 v[14:15], v[12:13], v[10:11]
	v_cvt_f32_i32_e32 v23, v168
	v_pk_mul_f32 v[16:17], v[14:15], v[14:15]
	v_cvt_f32_i32_e32 v22, v169
	v_pk_add_f32 v[12:13], v[14:15], v[12:13] neg_lo:[0,1] neg_hi:[0,1]
	v_pk_fma_f32 v[18:19], v[16:17], s[8:9], v[20:21] op_sel_hi:[1,0,0]
	v_pk_add_f32 v[10:11], v[10:11], v[12:13] neg_lo:[0,1] neg_hi:[0,1]
	v_ldexp_f32 v13, v15, 1
	v_pk_fma_f32 v[18:19], v[16:17], v[18:19], s[18:19] op_sel_hi:[1,1,0]
	v_ldexp_f32 v12, v14, 1
	v_pk_mul_f32 v[14:15], v[14:15], v[16:17]
	v_pk_mul_f32 v[16:17], v[22:23], s[28:29] op_sel_hi:[1,0]
	v_pk_mul_f32 v[14:15], v[14:15], v[18:19]
	v_pk_fma_f32 v[40:41], v[22:23], s[28:29], v[16:17] op_sel_hi:[1,0,1] neg_lo:[0,0,1] neg_hi:[0,0,1]
	v_pk_add_f32 v[18:19], v[12:13], v[14:15]
	v_ldexp_f32 v11, v11, 1
	v_pk_add_f32 v[12:13], v[18:19], v[12:13] neg_lo:[0,1] neg_hi:[0,1]
	v_pk_fma_f32 v[22:23], v[22:23], s[40:41], v[40:41] op_sel_hi:[1,0,1]
	v_pk_add_f32 v[12:13], v[14:15], v[12:13] neg_lo:[0,1] neg_hi:[0,1]
	v_ldexp_f32 v24, v10, 1
	v_mov_b32_e32 v14, v16
	v_mov_b32_e32 v15, v13
	v_mov_b32_e32 v10, v22
	v_mov_b32_e32 v25, v11
	v_pk_add_f32 v[14:15], v[14:15], v[10:11]
	v_pk_add_f32 v[10:11], v[24:25], v[12:13]
	v_mov_b32_e32 v13, v19
	v_mov_b32_e32 v25, v11
	v_pk_add_f32 v[40:41], v[16:17], v[22:23]
	v_pk_add_f32 v[12:13], v[24:25], v[12:13]
	v_pk_add_f32 v[24:25], v[18:19], v[10:11]
	v_mov_b32_e32 v170, v18
	v_pk_add_f32 v[166:167], v[40:41], v[24:25]
	v_mov_b32_e32 v168, v24
	v_mov_b32_e32 v169, v167
	v_mov_b32_e32 v171, v41
	v_pk_add_f32 v[168:169], v[168:169], v[170:171] neg_lo:[0,1] neg_hi:[0,1]
	v_mov_b32_e32 v170, v40
	v_mov_b32_e32 v171, v167
	v_mov_b32_e32 v172, v16
	v_mov_b32_e32 v173, v169
	v_pk_add_f32 v[170:171], v[170:171], v[172:173] neg_lo:[0,1] neg_hi:[0,1]
	v_mov_b32_e32 v173, v41
	v_mov_b32_e32 v174, v166
	v_mov_b32_e32 v175, v41
	v_mov_b32_e32 v41, v17
	v_mov_b32_e32 v172, v22
	v_pk_add_f32 v[16:17], v[174:175], v[40:41] neg_lo:[0,1] neg_hi:[0,1]
	v_pk_add_f32 v[172:173], v[172:173], v[170:171] neg_lo:[0,1] neg_hi:[0,1]
	v_mov_b32_e32 v171, v17
	v_pk_add_f32 v[40:41], v[22:23], v[170:171] neg_lo:[0,1] neg_hi:[0,1]
	v_pk_add_f32 v[170:171], v[24:25], v[18:19] neg_lo:[0,1] neg_hi:[0,1]
	v_pk_add_f32 v[12:13], v[12:13], v[168:169] neg_lo:[0,1] neg_hi:[0,1]
	v_mov_b32_e32 v168, v166
	v_mov_b32_e32 v169, v25
	v_mov_b32_e32 v18, v16
	v_pk_add_f32 v[18:19], v[168:169], v[18:19] neg_lo:[0,1] neg_hi:[0,1]
	v_mov_b32_e32 v25, v23
	v_pk_add_f32 v[14:15], v[14:15], v[18:19] neg_lo:[0,1] neg_hi:[0,1]
	v_pk_add_f32 v[16:17], v[24:25], v[16:17] neg_lo:[0,1] neg_hi:[0,1]
	v_pk_add_f32 v[22:23], v[12:13], v[172:173]
	v_mov_b32_e32 v173, v17
	v_mov_b32_e32 v13, v15
	v_pk_add_f32 v[18:19], v[16:17], v[14:15]
	v_pk_add_f32 v[12:13], v[172:173], v[12:13]
	v_mov_b32_e32 v14, v22
	v_pk_add_f32 v[12:13], v[12:13], v[40:41] neg_lo:[0,1] neg_hi:[0,1]
	v_mov_b32_e32 v15, v19
	v_pk_add_f32 v[10:11], v[10:11], v[170:171] neg_lo:[0,1] neg_hi:[0,1]
	v_pk_add_f32 v[14:15], v[14:15], v[12:13] neg_lo:[0,1] neg_hi:[0,1]
	v_pk_add_f32 v[10:11], v[10:11], v[12:13] neg_lo:[0,1] neg_hi:[0,1]
	v_pk_add_f32 v[14:15], v[172:173], v[14:15] neg_lo:[0,1] neg_hi:[0,1]
	v_pk_add_f32 v[12:13], v[18:19], v[22:23]
	v_pk_add_f32 v[10:11], v[10:11], v[14:15]
	v_pk_add_f32 v[14:15], v[166:167], v[12:13]
	global_load_dword v22, v[38:39], off
	global_load_dword v23, v[38:39], off offset:64
	global_load_dword v24, v[38:39], off offset:128
	global_load_dword v25, v[38:39], off offset:192
	v_pk_add_f32 v[16:17], v[14:15], v[166:167] neg_lo:[0,1] neg_hi:[0,1]
	global_load_dword v38, v[36:37], off
	global_load_dword v39, v[36:37], off offset:64
; template <int PASS>
; __device__ void lru_items(const Params& p, unsigned char* shm, int l) {
;     ...
;             for (int jt = 0; jt < 4; ++jt) { const int pi = (l * 2 + (w >> 2)) * 1024 + n * 64 + jt * 16 + fr; gba[jt] = p.in[7][pi]; gbx[jt] = p.in[9][pi]; gsp[jt] = -8.0f * log1pf(__expf(-p.in[10][pi])); }
	global_load_dword v40, v[36:37], off offset:128
	s_nop 0
	global_load_dword v36, v[36:37], off offset:192
	v_pk_add_f32 v[12:13], v[12:13], v[16:17] neg_lo:[0,1] neg_hi:[0,1]
	s_nop 0
	v_pk_add_f32 v[10:11], v[10:11], v[12:13]
	v_add_f32_e32 v12, 1.0, v0
	v_pk_add_f32 v[10:11], v[14:15], v[10:11]
	v_frexp_mant_f32_e32 v14, v12
	v_cndmask_b32_e32 v10, v237, v10, vcc
	v_cmp_neq_f32_e32 vcc, s1, v177
	s_nop 1
	v_cndmask_b32_e32 v11, v237, v11, vcc
	v_cmp_ngt_f32_e32 vcc, -1.0, v177
	s_nop 1
	v_cndmask_b32_e32 v11, v238, v11, vcc
	v_cmp_ngt_f32_e32 vcc, -1.0, v178
	s_nop 1
	v_cndmask_b32_e32 v10, v238, v10, vcc
	v_cmp_neq_f32_e32 vcc, -1.0, v178
	s_nop 1
	v_cndmask_b32_e32 v10, v239, v10, vcc
	v_cmp_neq_f32_e32 vcc, -1.0, v177
	s_nop 1
	v_cndmask_b32_e32 v11, v239, v11, vcc
	v_cmp_lt_f32_e64 vcc, |v177|, s5
	s_nop 1
	v_cndmask_b32_e32 v11, v11, v177, vcc
	v_cmp_lt_f32_e64 vcc, |v178|, s5
	s_nop 1
	v_cndmask_b32_e32 v10, v10, v178, vcc
	v_pk_mul_f32 v[18:19], v[10:11], s[48:49] op_sel_hi:[1,0]
	v_add_f32_e32 v10, -1.0, v12
	v_sub_f32_e32 v11, v10, v12
	v_add_f32_e32 v11, 1.0, v11
	v_sub_f32_e32 v10, v0, v10
	v_add_f32_e32 v13, v10, v11
	v_cvt_f64_f32_e32 v[10:11], v12
	v_frexp_exp_i32_f64_e32 v10, v[10:11]
	v_cmp_gt_f32_e32 vcc, s0, v14
	s_nop 1
	v_subbrev_co_u32_e32 v41, vcc, 0, v10, vcc
	v_sub_u32_e32 v10, 0, v41
	v_ldexp_f32 v11, v12, v10
	v_ldexp_f32 v13, v13, v10
	s_waitcnt vmcnt(8)
	v_mul_f32_e32 v10, 0xbfb8aa3b, v176
	v_exp_f32_e32 v182, v10
	s_nop 0
	v_add_f32_e32 v10, 1.0, v182
	v_add_f32_e32 v12, -1.0, v10
	v_sub_f32_e32 v14, v12, v10
	v_add_f32_e32 v14, 1.0, v14
	v_sub_f32_e32 v12, v182, v12
	v_add_f32_e32 v12, v12, v14
	v_frexp_mant_f32_e32 v16, v10
	v_cvt_f64_f32_e32 v[14:15], v10
	v_frexp_exp_i32_f64_e32 v14, v[14:15]
	v_cmp_gt_f32_e32 vcc, s0, v16
	s_nop 1
	v_subbrev_co_u32_e32 v37, vcc, 0, v14, vcc
	v_sub_u32_e32 v14, 0, v37
	v_ldexp_f32 v10, v10, v14
	v_ldexp_f32 v12, v12, v14
	v_pk_add_f32 v[14:15], v[10:11], 1.0 op_sel_hi:[1,0]
	v_pk_add_f32 v[170:171], v[10:11], -1.0 op_sel_hi:[1,0]
	v_pk_add_f32 v[16:17], v[14:15], -1.0 op_sel_hi:[1,0]
	v_pk_add_f32 v[172:173], v[170:171], 1.0 op_sel_hi:[1,0]
	v_pk_add_f32 v[16:17], v[10:11], v[16:17] neg_lo:[0,1] neg_hi:[0,1]
	v_pk_add_f32 v[10:11], v[10:11], v[172:173] neg_lo:[0,1] neg_hi:[0,1]
	v_pk_add_f32 v[16:17], v[12:13], v[16:17]
	v_pk_add_f32 v[10:11], v[12:13], v[10:11]
	v_pk_add_f32 v[166:167], v[14:15], v[16:17]
	v_pk_add_f32 v[12:13], v[170:171], v[10:11]
	v_rcp_f32_e32 v169, v167
	v_rcp_f32_e32 v168, v166
	v_pk_add_f32 v[14:15], v[166:167], v[14:15] neg_lo:[0,1] neg_hi:[0,1]
	v_pk_add_f32 v[170:171], v[12:13], v[170:171] neg_lo:[0,1] neg_hi:[0,1]
	v_pk_add_f32 v[14:15], v[16:17], v[14:15] neg_lo:[0,1] neg_hi:[0,1]
	v_pk_mul_f32 v[16:17], v[12:13], v[168:169]
	v_pk_add_f32 v[10:11], v[10:11], v[170:171] neg_lo:[0,1] neg_hi:[0,1]
	v_pk_mul_f32 v[170:171], v[166:167], v[16:17]
	v_cmp_neq_f32_e32 vcc, s1, v182
	v_pk_fma_f32 v[172:173], v[16:17], v[166:167], v[170:171] neg_lo:[0,0,1] neg_hi:[0,0,1]
	s_nop 0
	v_pk_fma_f32 v[172:173], v[16:17], v[14:15], v[172:173]
	s_nop 0
	v_pk_add_f32 v[174:175], v[170:171], v[172:173]
	s_nop 0
	v_pk_add_f32 v[176:177], v[12:13], v[174:175] neg_lo:[0,1] neg_hi:[0,1]
	v_pk_add_f32 v[170:171], v[174:175], v[170:171] neg_lo:[0,1] neg_hi:[0,1]
	v_pk_add_f32 v[12:13], v[12:13], v[176:177] neg_lo:[0,1] neg_hi:[0,1]
	s_nop 0
	v_pk_add_f32 v[12:13], v[12:13], v[174:175] neg_lo:[0,1] neg_hi:[0,1]
	s_nop 0
	v_pk_add_f32 v[10:11], v[10:11], v[12:13]
	v_pk_add_f32 v[12:13], v[170:171], v[172:173] neg_lo:[0,1] neg_hi:[0,1]
	s_nop 0
	v_pk_add_f32 v[10:11], v[12:13], v[10:11]
	s_nop 0
	v_pk_add_f32 v[12:13], v[176:177], v[10:11]
	s_nop 0
	v_pk_mul_f32 v[170:171], v[168:169], v[12:13]
	s_nop 0
	v_pk_mul_f32 v[172:173], v[166:167], v[170:171]
	s_nop 0
	v_pk_fma_f32 v[166:167], v[170:171], v[166:167], v[172:173] neg_lo:[0,0,1] neg_hi:[0,0,1]
	s_nop 0
	v_pk_fma_f32 v[14:15], v[170:171], v[14:15], v[166:167]
	v_pk_add_f32 v[166:167], v[176:177], v[12:13] neg_lo:[0,1] neg_hi:[0,1]
	s_nop 0
	v_pk_add_f32 v[10:11], v[10:11], v[166:167]
	v_pk_add_f32 v[166:167], v[172:173], v[14:15]
	s_nop 0
	v_pk_add_f32 v[174:175], v[12:13], v[166:167] neg_lo:[0,1] neg_hi:[0,1]
	v_pk_add_f32 v[172:173], v[166:167], v[172:173] neg_lo:[0,1] neg_hi:[0,1]
	v_pk_add_f32 v[12:13], v[12:13], v[174:175] neg_lo:[0,1] neg_hi:[0,1]
	s_nop 0
	v_pk_add_f32 v[12:13], v[12:13], v[166:167] neg_lo:[0,1] neg_hi:[0,1]
	v_cvt_f32_i32_e32 v167, v41
	v_pk_add_f32 v[10:11], v[10:11], v[12:13]
	v_pk_add_f32 v[12:13], v[172:173], v[14:15] neg_lo:[0,1] neg_hi:[0,1]
	v_cvt_f32_i32_e32 v166, v37
	v_pk_add_f32 v[10:11], v[12:13], v[10:11]
	v_pk_add_f32 v[12:13], v[16:17], v[170:171]
	v_pk_add_f32 v[10:11], v[174:175], v[10:11]
	v_pk_add_f32 v[14:15], v[12:13], v[16:17] neg_lo:[0,1] neg_hi:[0,1]
	v_pk_mul_f32 v[10:11], v[168:169], v[10:11]
; __device__ __forceinline__ float sigm(float x) { return __builtin_amdgcn_rcpf(1.0f + __expf(-x)); }
; template <int PASS>
; __device__ void lru_items(const Params& p, unsigned char* shm, int l) {
;     ...
;             { const int ch = n * 64 + (tid & 63); c0 = cw[ch]; c1 = cw[1024 + ch]; c2 = cw[2048 + ch]; c3 = cw[3072 + ch]; cb = cbias[ch]; }
; #pragma unroll
;             for (int jt = 0; jt < 4; ++jt) { const int pi = (l * 2 + (w >> 2)) * 1024 + n * 64 + jt * 16 + fr; gba[jt] = p.in[7][pi]; gbx[jt] = p.in[9][pi]; gsp[jt] = -8.0f * log1pf(__expf(-p.in[10][pi])); }
;     ...
;                   const float r = sigm(accr[i] + gba[jt]), ig = sigm(acci[i] + gbx[jt]), a = __expf(r * gsp[jt]);
	v_pk_add_f32 v[14:15], v[170:171], v[14:15] neg_lo:[0,1] neg_hi:[0,1]
	s_nop 0
	v_pk_add_f32 v[10:11], v[14:15], v[10:11]
	s_nop 0
	v_pk_add_f32 v[14:15], v[12:13], v[10:11]
	s_nop 0
	v_pk_mul_f32 v[16:17], v[14:15], v[14:15]
	v_pk_add_f32 v[12:13], v[14:15], v[12:13] neg_lo:[0,1] neg_hi:[0,1]
	v_pk_fma_f32 v[20:21], v[16:17], s[8:9], v[20:21] op_sel_hi:[1,0,0]
	v_pk_add_f32 v[10:11], v[10:11], v[12:13] neg_lo:[0,1] neg_hi:[0,1]
	v_ldexp_f32 v13, v15, 1
	v_pk_fma_f32 v[20:21], v[16:17], v[20:21], s[18:19] op_sel_hi:[1,1,0]
	v_ldexp_f32 v12, v14, 1
	v_pk_mul_f32 v[14:15], v[14:15], v[16:17]
	v_pk_mul_f32 v[16:17], v[166:167], s[28:29] op_sel_hi:[1,0]
	v_pk_mul_f32 v[14:15], v[14:15], v[20:21]
	v_pk_fma_f32 v[170:171], v[166:167], s[28:29], v[16:17] op_sel_hi:[1,0,1] neg_lo:[0,0,1] neg_hi:[0,0,1]
	v_pk_add_f32 v[20:21], v[12:13], v[14:15]
	v_ldexp_f32 v11, v11, 1
	v_pk_add_f32 v[12:13], v[20:21], v[12:13] neg_lo:[0,1] neg_hi:[0,1]
	v_pk_fma_f32 v[166:167], v[166:167], s[40:41], v[170:171] op_sel_hi:[1,0,1]
	v_pk_add_f32 v[12:13], v[14:15], v[12:13] neg_lo:[0,1] neg_hi:[0,1]
	v_ldexp_f32 v168, v10, 1
	v_mov_b32_e32 v14, v16
	v_mov_b32_e32 v15, v13
	v_mov_b32_e32 v10, v166
	v_mov_b32_e32 v169, v11
	v_pk_add_f32 v[14:15], v[14:15], v[10:11]
	v_pk_add_f32 v[10:11], v[168:169], v[12:13]
	v_mov_b32_e32 v13, v21
	v_mov_b32_e32 v169, v11
	v_pk_add_f32 v[170:171], v[16:17], v[166:167]
	v_pk_add_f32 v[12:13], v[168:169], v[12:13]
	v_pk_add_f32 v[168:169], v[20:21], v[10:11]
	v_mov_b32_e32 v176, v20
	v_pk_add_f32 v[172:173], v[170:171], v[168:169]
	v_mov_b32_e32 v174, v168
	v_mov_b32_e32 v175, v173
	v_mov_b32_e32 v177, v171
	v_pk_add_f32 v[174:175], v[174:175], v[176:177] neg_lo:[0,1] neg_hi:[0,1]
	v_mov_b32_e32 v176, v170
	v_mov_b32_e32 v177, v173
	v_mov_b32_e32 v178, v16
	v_mov_b32_e32 v179, v175
	v_pk_add_f32 v[176:177], v[176:177], v[178:179] neg_lo:[0,1] neg_hi:[0,1]
	v_mov_b32_e32 v179, v171
	v_mov_b32_e32 v180, v172
	v_mov_b32_e32 v181, v171
	v_mov_b32_e32 v171, v17
	v_mov_b32_e32 v178, v166
	v_pk_add_f32 v[16:17], v[180:181], v[170:171] neg_lo:[0,1] neg_hi:[0,1]
	v_pk_add_f32 v[178:179], v[178:179], v[176:177] neg_lo:[0,1] neg_hi:[0,1]
	v_mov_b32_e32 v177, v17
	v_pk_add_f32 v[170:171], v[166:167], v[176:177] neg_lo:[0,1] neg_hi:[0,1]
	v_pk_add_f32 v[176:177], v[168:169], v[20:21] neg_lo:[0,1] neg_hi:[0,1]
	v_pk_add_f32 v[12:13], v[12:13], v[174:175] neg_lo:[0,1] neg_hi:[0,1]
	v_mov_b32_e32 v174, v172
	v_mov_b32_e32 v175, v169
	v_mov_b32_e32 v20, v16
	v_pk_add_f32 v[20:21], v[174:175], v[20:21] neg_lo:[0,1] neg_hi:[0,1]
	v_mov_b32_e32 v169, v167
	v_pk_add_f32 v[14:15], v[14:15], v[20:21] neg_lo:[0,1] neg_hi:[0,1]
	v_pk_add_f32 v[16:17], v[168:169], v[16:17] neg_lo:[0,1] neg_hi:[0,1]
	v_pk_add_f32 v[166:167], v[12:13], v[178:179]
	v_mov_b32_e32 v179, v17
	v_mov_b32_e32 v13, v15
	v_pk_add_f32 v[20:21], v[16:17], v[14:15]
	v_pk_add_f32 v[12:13], v[178:179], v[12:13]
	v_mov_b32_e32 v14, v166
	v_pk_add_f32 v[12:13], v[12:13], v[170:171] neg_lo:[0,1] neg_hi:[0,1]
	v_mov_b32_e32 v15, v21
	v_pk_add_f32 v[10:11], v[10:11], v[176:177] neg_lo:[0,1] neg_hi:[0,1]
	v_pk_add_f32 v[14:15], v[14:15], v[12:13] neg_lo:[0,1] neg_hi:[0,1]
	v_pk_add_f32 v[10:11], v[10:11], v[12:13] neg_lo:[0,1] neg_hi:[0,1]
	v_pk_add_f32 v[14:15], v[178:179], v[14:15] neg_lo:[0,1] neg_hi:[0,1]
	v_pk_add_f32 v[12:13], v[20:21], v[166:167]
	v_pk_add_f32 v[10:11], v[10:11], v[14:15]
	v_pk_add_f32 v[14:15], v[172:173], v[12:13]
	s_nop 0
	v_pk_add_f32 v[16:17], v[14:15], v[172:173] neg_lo:[0,1] neg_hi:[0,1]
	s_nop 0
	v_pk_add_f32 v[12:13], v[12:13], v[16:17] neg_lo:[0,1] neg_hi:[0,1]
	s_nop 0
	v_pk_add_f32 v[10:11], v[10:11], v[12:13]
	s_nop 0
	v_pk_add_f32 v[10:11], v[14:15], v[10:11]
	s_nop 0
	v_cndmask_b32_e32 v10, v237, v10, vcc
	v_cmp_neq_f32_e32 vcc, s1, v0
	s_mov_b64 s[0:1], 0
	s_nop 0
	v_cndmask_b32_e32 v11, v237, v11, vcc
	v_cmp_ngt_f32_e32 vcc, -1.0, v0
	s_nop 1
	v_cndmask_b32_e32 v11, v238, v11, vcc
	v_cmp_ngt_f32_e32 vcc, -1.0, v182
	s_nop 1
	v_cndmask_b32_e32 v10, v238, v10, vcc
	v_cmp_neq_f32_e32 vcc, -1.0, v182
	s_nop 1
	v_cndmask_b32_e32 v10, v239, v10, vcc
	v_cmp_neq_f32_e32 vcc, -1.0, v0
	s_nop 1
	v_cndmask_b32_e32 v11, v239, v11, vcc
	v_cmp_lt_f32_e64 vcc, |v0|, s5
	s_nop 1
	v_cndmask_b32_e32 v11, v11, v0, vcc
	v_cmp_lt_f32_e64 vcc, |v182|, s5
	s_nop 1
	v_cndmask_b32_e32 v10, v10, v182, vcc
	v_pk_mul_f32 v[20:21], v[10:11], s[48:49] op_sel_hi:[1,0]
	s_waitcnt vmcnt(0)
	v_mul_f32_e32 v22, 0xbfb8aa3b, v22
	v_mul_f32_e32 v23, 0xbfb8aa3b, v23
	v_mul_f32_e32 v24, 0xbfb8aa3b, v24
	v_mul_f32_e32 v25, 0xbfb8aa3b, v25
	v_mul_f32_e32 v36, 0xbfb8aa3b, v36
	v_mul_f32_e32 v38, 0xbfb8aa3b, v38
	v_mul_f32_e32 v39, 0xbfb8aa3b, v39
	v_mul_f32_e32 v40, 0xbfb8aa3b, v40
	v_mul_f32_e32 v18, 0x3fb8aa3b, v18
	v_mul_f32_e32 v19, 0x3fb8aa3b, v19
	v_mul_f32_e32 v20, 0x3fb8aa3b, v20
	v_mul_f32_e32 v21, 0x3fb8aa3b, v21

; __device__ __forceinline__ bf16_t f2bf(float f) { return (bf16_t)(cvt_pk_bf16(f, 0.f) & 0xffffu); }
; __device__ __forceinline__ float bf2f(bf16_t b) { return __uint_as_float(((unsigned)b) << 16); }
; __device__ __forceinline__ float sigm(float x) { return __builtin_amdgcn_rcpf(1.0f + __expf(-x)); }
; template <int PASS>
; __device__ void lru_items(const Params& p, unsigned char* shm, int l) {
;     ...
;         { const int j = tid & 63;
; #pragma unroll
;           for (int i = 0; i < 8; ++i) { const int t = (tid >> 6) + 8 * i;
;               const float v = cb + bf2f(xraw[t * 64 + j]) * c0 + bf2f(xraw[(t + 1) * 64 + j]) * c1 + bf2f(xraw[(t + 2) * 64 + j]) * c2 + bf2f(xraw[(t + 3) * 64 + j]) * c3;
;               xcf[t * 65 + j] = v; xcb[t * 72 + j] = f2bf(v); } }
;         __syncthreads();
;         { const int d = w >> 2, tt = w & 3;
;           const bf16x8 a0 = *(const bf16x8*)(xcb + (tt * 16 + fr) * 72 + fq * 8), a1 = *(const bf16x8*)(xcb + (tt * 16 + fr) * 72 + 32 + fq * 8);
; #pragma unroll
;           for (int jt = 0; jt < 4; ++jt) {
;               f32x4 accr = (f32x4){0.f, 0.f, 0.f, 0.f}, acci = (f32x4){0.f, 0.f, 0.f, 0.f};
;               const bf16_t* wr_ = wt + ((d * 2 + 0) * 64 + jt * 16 + fr) * 72 + fq * 8; const bf16_t* wi_ = wt + ((d * 2 + 1) * 64 + jt * 16 + fr) * 72 + fq * 8;
;               accr = __builtin_amdgcn_mfma_f32_16x16x32_bf16(a0, *(const bf16x8*)wr_, accr, 0, 0, 0);
;               accr = __builtin_amdgcn_mfma_f32_16x16x32_bf16(a1, *(const bf16x8*)(wr_ + 32), accr, 0, 0, 0);
;               acci = __builtin_amdgcn_mfma_f32_16x16x32_bf16(a0, *(const bf16x8*)wi_, acci, 0, 0, 0);
;               acci = __builtin_amdgcn_mfma_f32_16x16x32_bf16(a1, *(const bf16x8*)(wi_ + 32), acci, 0, 0, 0);
;               const int j = jt * 16 + fr;
; #pragma unroll
;               for (int i = 0; i < 4; ++i) { const int t = tt * 16 + fq * 4 + i;
;                   const float r = sigm(accr[i] + gba[jt]), ig = sigm(acci[i] + gbx[jt]), a = __expf(r * gsp[jt]);
;                   As[(d * 64 + t) * 64 + j] = a;
;                   Bs[(d * 64 + t) * 64 + j] = sqrtf(fmaxf(1.0f - a * a, 0.f)) * ig * xcf[t * 65 + j]; }
.LBB0_310:
	s_mov_b32 s0, 0xf800000
	v_lshrrev_b32_e32 v183, 6, v229
	v_and_b32_e32 v184, 63, v229
	v_lshlrev_b32_e32 v185, 10, v183
	v_lshl_add_u32 v185, v184, 1, v185
	ds_read_u16 v186, v185
	ds_read_u16 v187, v185 offset:128
	ds_read_u16 v188, v185 offset:256
	ds_read_u16 v189, v185 offset:384
	ds_read_u16 v190, v185 offset:512
	ds_read_u16 v191, v185 offset:640
	ds_read_u16 v192, v185 offset:768
	ds_read_u16 v193, v185 offset:896
	ds_read_u16 v194, v185 offset:1024
	ds_read_u16 v196, v185 offset:1152
	ds_read_u16 v197, v185 offset:1280
	v_mul_u32_u24_e32 v206, 0x820, v183
	v_lshl_add_u32 v206, v184, 2, v206
	v_mul_u32_u24_e32 v207, 0x480, v183
	v_lshl_add_u32 v207, v184, 1, v207
	s_waitcnt lgkmcnt(0)
	v_lshlrev_b32_e32 v186, 16, v186
	v_lshlrev_b32_e32 v187, 16, v187
	v_lshlrev_b32_e32 v188, 16, v188
	v_lshlrev_b32_e32 v189, 16, v189
	v_lshlrev_b32_e32 v190, 16, v190
	v_lshlrev_b32_e32 v191, 16, v191
	v_lshlrev_b32_e32 v192, 16, v192
	v_lshlrev_b32_e32 v193, 16, v193
	v_lshlrev_b32_e32 v194, 16, v194
	v_lshlrev_b32_e32 v196, 16, v196
	v_lshlrev_b32_e32 v197, 16, v197
	v_fma_f32 v198, v149, v186, v148
	v_fma_f32 v199, v149, v187, v148
	v_fma_f32 v200, v149, v188, v148
	v_fma_f32 v201, v149, v189, v148
	v_fma_f32 v202, v149, v190, v148
	v_fma_f32 v203, v149, v191, v148
	v_fma_f32 v204, v149, v192, v148
	v_fma_f32 v205, v149, v193, v148
	v_fmac_f32_e32 v198, v152, v187
	v_fmac_f32_e32 v199, v152, v188
	v_fmac_f32_e32 v200, v152, v189
	v_fmac_f32_e32 v201, v152, v190
	v_fmac_f32_e32 v202, v152, v191
	v_fmac_f32_e32 v203, v152, v192
	v_fmac_f32_e32 v204, v152, v193
	v_fmac_f32_e32 v205, v152, v194
	v_fmac_f32_e32 v198, v151, v188
	v_fmac_f32_e32 v199, v151, v189
	v_fmac_f32_e32 v200, v151, v190
	v_fmac_f32_e32 v201, v151, v191
	v_fmac_f32_e32 v202, v151, v192
	v_fmac_f32_e32 v203, v151, v193
	v_fmac_f32_e32 v204, v151, v194
	v_fmac_f32_e32 v205, v151, v196
	v_fmac_f32_e32 v198, v150, v189
	v_fmac_f32_e32 v199, v150, v190
	v_fmac_f32_e32 v200, v150, v191
	v_fmac_f32_e32 v201, v150, v192
	v_fmac_f32_e32 v202, v150, v193
	v_fmac_f32_e32 v203, v150, v194
	v_fmac_f32_e32 v204, v150, v196
	v_fmac_f32_e32 v205, v150, v197
	ds_write_b32 v206, v198 offset:8704
	ds_write_b32 v206, v199 offset:8964
	ds_write_b32 v206, v200 offset:9224
	ds_write_b32 v206, v201 offset:9484
	ds_write_b32 v206, v202 offset:9744
	ds_write_b32 v206, v203 offset:10004
	ds_write_b32 v206, v204 offset:10264
	ds_write_b32 v206, v205 offset:10524
	v_cvt_pk_bf16_f32 v186, v198, v1
	v_cvt_pk_bf16_f32 v187, v199, v1
	ds_write_b16 v207, v186 offset:25344
	v_cvt_pk_bf16_f32 v188, v200, v1
	ds_write_b16 v207, v187 offset:25488
	v_cvt_pk_bf16_f32 v189, v201, v1
	ds_write_b16 v207, v188 offset:25632
	v_cvt_pk_bf16_f32 v190, v202, v1
	ds_write_b16 v207, v189 offset:25776
	v_cvt_pk_bf16_f32 v191, v203, v1
	ds_write_b16 v207, v190 offset:25920
	v_cvt_pk_bf16_f32 v192, v204, v1
	ds_write_b16 v207, v191 offset:26064
	v_cvt_pk_bf16_f32 v193, v205, v1
	ds_write_b16 v207, v192 offset:26208
	ds_write_b16 v207, v193 offset:26352
	s_waitcnt lgkmcnt(0)
	s_barrier
	ds_read_b128 v[14:17], v44 offset:25344
	ds_read_b128 v[10:13], v44 offset:25408
	ds_read_b128 v[32:35], v67 offset:34560
	ds_read_b128 v[154:157], v67 offset:34624
	s_waitcnt lgkmcnt(1)
	v_mfma_f32_16x16x32_bf16 v[32:35], v[14:17], v[32:35], 0
	ds_read_b128 v[158:161], v68 offset:43840
	s_waitcnt lgkmcnt(1)
	v_mfma_f32_16x16x32_bf16 v[32:35], v[10:13], v[154:157], v[32:35]
	ds_read_b128 v[154:157], v68 offset:43776
	s_waitcnt lgkmcnt(0)
	v_mfma_f32_16x16x32_bf16 v[154:157], v[14:17], v[154:157], 0
	s_waitcnt vmcnt(7)
	s_nop 3
	v_fmamk_f32 v0, v32, 0xbfb8aa3b, v22
	v_exp_f32_e32 v0, v0
	v_mfma_f32_16x16x32_bf16 v[154:157], v[10:13], v[158:161], v[154:157]
	v_fmamk_f32 v33, v33, 0xbfb8aa3b, v22
	v_add_f32_e32 v0, 1.0, v0
	v_rcp_f32_e32 v0, v0
	v_exp_f32_e32 v33, v33
	s_waitcnt vmcnt(3)
	s_nop 2
	v_fmamk_f32 v32, v154, 0xbfb8aa3b, v38
	v_mul_f32_e32 v0, v19, v0
	v_exp_f32_e32 v0, v0
	v_exp_f32_e32 v32, v32
	v_add_f32_e32 v33, 1.0, v33
	v_rcp_f32_e32 v33, v33
	v_fma_f32 v37, -v0, v0, 1.0
	v_max_f32_e32 v37, 0, v37
	ds_write_b32 v69, v0
	v_add_f32_e32 v32, 1.0, v32
	v_sqrt_f32_e32 v41, v37
	v_rcp_f32_e32 v32, v32
	v_fmamk_f32 v34, v34, 0xbfb8aa3b, v22
	v_mov_b32_e32 v0, v41
	v_exp_f32_e32 v34, v34
	ds_read_b32 v41, v147 offset:8704
	v_mul_f32_e32 v0, v32, v0
	s_waitcnt lgkmcnt(0)
	v_mul_f32_e32 v0, v41, v0
	ds_write_b32 v70, v0
	v_mul_f32_e32 v0, v19, v33
	v_exp_f32_e32 v0, v0
	v_fmamk_f32 v32, v155, 0xbfb8aa3b, v38
	v_exp_f32_e32 v32, v32
	v_fma_f32 v33, -v0, v0, 1.0
	v_max_f32_e32 v33, 0, v33
	ds_write_b32 v71, v0
	v_add_f32_e32 v32, 1.0, v32
	v_sqrt_f32_e32 v37, v33
	v_rcp_f32_e32 v32, v32
	v_mov_b32_e32 v0, v37
	ds_read_b32 v37, v147 offset:8964
	v_add_f32_e32 v33, 1.0, v34
	v_rcp_f32_e32 v33, v33
	v_mul_f32_e32 v0, v32, v0
	s_waitcnt lgkmcnt(0)
	v_mul_f32_e32 v0, v37, v0
	ds_write_b32 v72, v0
	v_mul_f32_e32 v0, v19, v33
	v_exp_f32_e32 v0, v0
	v_fmamk_f32 v32, v156, 0xbfb8aa3b, v38
	v_exp_f32_e32 v32, v32
	v_fma_f32 v33, -v0, v0, 1.0
	v_max_f32_e32 v33, 0, v33
	ds_write_b32 v73, v0
	v_add_f32_e32 v32, 1.0, v32
	v_sqrt_f32_e32 v34, v33
	v_rcp_f32_e32 v32, v32
	v_mov_b32_e32 v0, v34
	v_fmamk_f32 v34, v35, 0xbfb8aa3b, v22
	v_exp_f32_e32 v34, v34
	ds_read_b32 v35, v147 offset:9224
	v_add_f32_e32 v33, 1.0, v34
	v_rcp_f32_e32 v33, v33
	v_mul_f32_e32 v0, v32, v0
	s_waitcnt lgkmcnt(0)
	v_mul_f32_e32 v0, v35, v0
	ds_write_b32 v74, v0
	v_mul_f32_e32 v0, v19, v33
	v_exp_f32_e32 v0, v0
	v_fmamk_f32 v32, v157, 0xbfb8aa3b, v38
	v_exp_f32_e32 v32, v32
	v_fma_f32 v33, -v0, v0, 1.0
	v_max_f32_e32 v33, 0, v33
	ds_write_b32 v75, v0
	v_add_f32_e32 v32, 1.0, v32
	v_sqrt_f32_e32 v34, v33
	v_rcp_f32_e32 v32, v32
	v_mov_b32_e32 v0, v34
	ds_read_b32 v35, v147 offset:9484
	v_mul_f32_e32 v0, v32, v0
	s_waitcnt lgkmcnt(0)
; __device__ __forceinline__ float sigm(float x) { return __builtin_amdgcn_rcpf(1.0f + __expf(-x)); }
; template <int PASS>
; __device__ void lru_items(const Params& p, unsigned char* shm, int l) {
;     ...
;           for (int jt = 0; jt < 4; ++jt) {
;               f32x4 accr = (f32x4){0.f, 0.f, 0.f, 0.f}, acci = (f32x4){0.f, 0.f, 0.f, 0.f};
;               const bf16_t* wr_ = wt + ((d * 2 + 0) * 64 + jt * 16 + fr) * 72 + fq * 8; const bf16_t* wi_ = wt + ((d * 2 + 1) * 64 + jt * 16 + fr) * 72 + fq * 8;
;               accr = __builtin_amdgcn_mfma_f32_16x16x32_bf16(a0, *(const bf16x8*)wr_, accr, 0, 0, 0);
;               accr = __builtin_amdgcn_mfma_f32_16x16x32_bf16(a1, *(const bf16x8*)(wr_ + 32), accr, 0, 0, 0);
;               acci = __builtin_amdgcn_mfma_f32_16x16x32_bf16(a0, *(const bf16x8*)wi_, acci, 0, 0, 0);
;               acci = __builtin_amdgcn_mfma_f32_16x16x32_bf16(a1, *(const bf16x8*)(wi_ + 32), acci, 0, 0, 0);
;               const int j = jt * 16 + fr;
; #pragma unroll
;               for (int i = 0; i < 4; ++i) { const int t = tt * 16 + fq * 4 + i;
;                   const float r = sigm(accr[i] + gba[jt]), ig = sigm(acci[i] + gbx[jt]), a = __expf(r * gsp[jt]);
;                   As[(d * 64 + t) * 64 + j] = a;
;                   Bs[(d * 64 + t) * 64 + j] = sqrtf(fmaxf(1.0f - a * a, 0.f)) * ig * xcf[t * 65 + j]; }
	v_mul_f32_e32 v0, v0, v35
	ds_write_b32 v76, v0
	ds_read_b128 v[32:35], v67 offset:36864
	ds_read_b128 v[154:157], v67 offset:36928
	s_waitcnt lgkmcnt(1)
	v_mfma_f32_16x16x32_bf16 v[32:35], v[14:17], v[32:35], 0
	ds_read_b128 v[158:161], v68 offset:46144
	s_waitcnt lgkmcnt(1)
	v_mfma_f32_16x16x32_bf16 v[32:35], v[10:13], v[154:157], v[32:35]
	ds_read_b128 v[154:157], v68 offset:46080
	s_waitcnt lgkmcnt(0)
	v_mfma_f32_16x16x32_bf16 v[154:157], v[14:17], v[154:157], 0
	s_nop 4
	v_fmamk_f32 v0, v32, 0xbfb8aa3b, v23
	v_exp_f32_e32 v0, v0
	v_mfma_f32_16x16x32_bf16 v[154:157], v[10:13], v[158:161], v[154:157]
	v_fmamk_f32 v33, v33, 0xbfb8aa3b, v23
	v_add_f32_e32 v0, 1.0, v0
	v_rcp_f32_e32 v0, v0
	v_exp_f32_e32 v33, v33
	s_waitcnt vmcnt(2)
	s_nop 2
	v_fmamk_f32 v32, v154, 0xbfb8aa3b, v39
	v_mul_f32_e32 v0, v18, v0
	v_exp_f32_e32 v0, v0
	v_exp_f32_e32 v32, v32
	v_add_f32_e32 v33, 1.0, v33
	v_rcp_f32_e32 v33, v33
	v_fma_f32 v37, -v0, v0, 1.0
	v_max_f32_e32 v37, 0, v37
	ds_write_b32 v77, v0
	v_add_f32_e32 v32, 1.0, v32
	v_sqrt_f32_e32 v41, v37
	v_rcp_f32_e32 v32, v32
	v_fmamk_f32 v34, v34, 0xbfb8aa3b, v23
	v_mov_b32_e32 v0, v41
	v_exp_f32_e32 v34, v34
	ds_read_b32 v41, v147 offset:8768
	v_mul_f32_e32 v0, v32, v0
	s_waitcnt lgkmcnt(0)
	v_mul_f32_e32 v0, v41, v0
	ds_write_b32 v78, v0
	v_mul_f32_e32 v0, v18, v33
	v_exp_f32_e32 v0, v0
	v_fmamk_f32 v32, v155, 0xbfb8aa3b, v39
	v_exp_f32_e32 v32, v32
	v_fma_f32 v33, -v0, v0, 1.0
	v_max_f32_e32 v33, 0, v33
	ds_write_b32 v79, v0
	v_add_f32_e32 v32, 1.0, v32
	v_sqrt_f32_e32 v37, v33
	v_rcp_f32_e32 v32, v32
	v_mov_b32_e32 v0, v37
	ds_read_b32 v37, v147 offset:9028
	v_add_f32_e32 v33, 1.0, v34
	v_rcp_f32_e32 v33, v33
	v_mul_f32_e32 v0, v32, v0
	s_waitcnt lgkmcnt(0)
	v_mul_f32_e32 v0, v37, v0
	ds_write_b32 v80, v0
	v_mul_f32_e32 v0, v18, v33
	v_exp_f32_e32 v0, v0
	v_fmamk_f32 v32, v156, 0xbfb8aa3b, v39
	v_exp_f32_e32 v32, v32
	v_fma_f32 v33, -v0, v0, 1.0
	v_max_f32_e32 v33, 0, v33
	ds_write_b32 v81, v0
	v_add_f32_e32 v32, 1.0, v32
	v_sqrt_f32_e32 v34, v33
	v_rcp_f32_e32 v32, v32
	v_mov_b32_e32 v0, v34
	v_fmamk_f32 v34, v35, 0xbfb8aa3b, v23
	v_exp_f32_e32 v34, v34
	ds_read_b32 v35, v147 offset:9288
	v_add_f32_e32 v33, 1.0, v34
	v_rcp_f32_e32 v33, v33
	v_mul_f32_e32 v0, v32, v0
	s_waitcnt lgkmcnt(0)
	v_mul_f32_e32 v0, v35, v0
	ds_write_b32 v82, v0
	v_mul_f32_e32 v0, v18, v33
	v_exp_f32_e32 v0, v0
	v_fmamk_f32 v32, v157, 0xbfb8aa3b, v39
	v_exp_f32_e32 v32, v32
	v_fma_f32 v33, -v0, v0, 1.0
	v_max_f32_e32 v33, 0, v33
	ds_write_b32 v83, v0
	v_add_f32_e32 v32, 1.0, v32
	v_sqrt_f32_e32 v34, v33
	v_rcp_f32_e32 v32, v32
	v_mov_b32_e32 v0, v34
	ds_read_b32 v35, v147 offset:9548
	v_mul_f32_e32 v0, v32, v0
	s_waitcnt lgkmcnt(0)
	v_mul_f32_e32 v0, v0, v35
	ds_write_b32 v84, v0
	ds_read_b128 v[32:35], v67 offset:39168
	ds_read_b128 v[154:157], v67 offset:39232
	s_waitcnt lgkmcnt(1)
	v_mfma_f32_16x16x32_bf16 v[32:35], v[14:17], v[32:35], 0
	ds_read_b128 v[158:161], v68 offset:48448
	s_waitcnt lgkmcnt(1)
	v_mfma_f32_16x16x32_bf16 v[32:35], v[10:13], v[154:157], v[32:35]
	ds_read_b128 v[154:157], v68 offset:48384
	s_waitcnt lgkmcnt(0)
	v_mfma_f32_16x16x32_bf16 v[154:157], v[14:17], v[154:157], 0
	s_nop 4
	v_fmamk_f32 v0, v32, 0xbfb8aa3b, v24
	v_exp_f32_e32 v0, v0
	v_mfma_f32_16x16x32_bf16 v[154:157], v[10:13], v[158:161], v[154:157]
	v_fmamk_f32 v33, v33, 0xbfb8aa3b, v24
	v_add_f32_e32 v0, 1.0, v0
	v_rcp_f32_e32 v0, v0
	v_exp_f32_e32 v33, v33
	s_waitcnt vmcnt(1)
	s_nop 2
	v_fmamk_f32 v32, v154, 0xbfb8aa3b, v40
	v_mul_f32_e32 v0, v21, v0
	v_exp_f32_e32 v0, v0
	v_exp_f32_e32 v32, v32
	v_add_f32_e32 v33, 1.0, v33
	v_rcp_f32_e32 v33, v33
	v_fma_f32 v37, -v0, v0, 1.0
	v_max_f32_e32 v37, 0, v37
	ds_write_b32 v85, v0
	v_add_f32_e32 v32, 1.0, v32
	v_sqrt_f32_e32 v41, v37
	v_rcp_f32_e32 v32, v32
	v_fmamk_f32 v34, v34, 0xbfb8aa3b, v24
	v_mov_b32_e32 v0, v41
	v_exp_f32_e32 v34, v34
	ds_read_b32 v41, v147 offset:8832
	v_mul_f32_e32 v0, v32, v0
	s_waitcnt lgkmcnt(0)
	v_mul_f32_e32 v0, v41, v0
	ds_write_b32 v86, v0
	v_mul_f32_e32 v0, v21, v33
	v_exp_f32_e32 v0, v0
	v_fmamk_f32 v32, v155, 0xbfb8aa3b, v40
	v_exp_f32_e32 v32, v32
	v_fma_f32 v33, -v0, v0, 1.0
	v_max_f32_e32 v33, 0, v33
	ds_write_b32 v87, v0
	v_add_f32_e32 v32, 1.0, v32
	v_sqrt_f32_e32 v37, v33
	v_rcp_f32_e32 v32, v32
	v_mov_b32_e32 v0, v37
	ds_read_b32 v37, v147 offset:9092
	v_add_f32_e32 v33, 1.0, v34
	v_rcp_f32_e32 v33, v33
	v_mul_f32_e32 v0, v32, v0
	s_waitcnt lgkmcnt(0)
	v_mul_f32_e32 v0, v37, v0
	ds_write_b32 v88, v0
	v_mul_f32_e32 v0, v21, v33
	v_exp_f32_e32 v0, v0
	v_fmamk_f32 v32, v156, 0xbfb8aa3b, v40
	v_exp_f32_e32 v32, v32
	v_fma_f32 v33, -v0, v0, 1.0
	v_max_f32_e32 v33, 0, v33
	ds_write_b32 v89, v0
	v_add_f32_e32 v32, 1.0, v32
	v_sqrt_f32_e32 v34, v33
	v_rcp_f32_e32 v32, v32
	v_mov_b32_e32 v0, v34
	v_fmamk_f32 v34, v35, 0xbfb8aa3b, v24
	v_exp_f32_e32 v34, v34
	ds_read_b32 v35, v147 offset:9352
	v_add_f32_e32 v33, 1.0, v34
	v_rcp_f32_e32 v33, v33
	v_mul_f32_e32 v0, v32, v0
	s_waitcnt lgkmcnt(0)
	v_mul_f32_e32 v0, v35, v0
	ds_write_b32 v90, v0
	v_mul_f32_e32 v0, v21, v33
	v_exp_f32_e32 v0, v0
	v_fmamk_f32 v32, v157, 0xbfb8aa3b, v40
	v_exp_f32_e32 v32, v32
	v_fma_f32 v33, -v0, v0, 1.0
	v_max_f32_e32 v33, 0, v33
	ds_write_b32 v91, v0
	v_add_f32_e32 v32, 1.0, v32
	v_sqrt_f32_e32 v34, v33
	v_rcp_f32_e32 v32, v32
	v_mov_b32_e32 v0, v34
	ds_read_b32 v35, v147 offset:9612
	v_mul_f32_e32 v0, v32, v0
	s_waitcnt lgkmcnt(0)
	v_mul_f32_e32 v0, v0, v35
	ds_write_b32 v92, v0
	ds_read_b128 v[32:35], v67 offset:41472
	ds_read_b128 v[154:157], v67 offset:41536
	s_waitcnt lgkmcnt(1)
	v_mfma_f32_16x16x32_bf16 v[32:35], v[14:17], v[32:35], 0
	ds_read_b128 v[158:161], v68 offset:50752
	s_waitcnt lgkmcnt(1)
; __device__ __forceinline__ float sigm(float x) { return __builtin_amdgcn_rcpf(1.0f + __expf(-x)); }
; template <int PASS>
; __device__ void lru_items(const Params& p, unsigned char* shm, int l) {
;     ...
;           for (int jt = 0; jt < 4; ++jt) {
;               f32x4 accr = (f32x4){0.f, 0.f, 0.f, 0.f}, acci = (f32x4){0.f, 0.f, 0.f, 0.f};
;               const bf16_t* wr_ = wt + ((d * 2 + 0) * 64 + jt * 16 + fr) * 72 + fq * 8; const bf16_t* wi_ = wt + ((d * 2 + 1) * 64 + jt * 16 + fr) * 72 + fq * 8;
;               accr = __builtin_amdgcn_mfma_f32_16x16x32_bf16(a0, *(const bf16x8*)wr_, accr, 0, 0, 0);
;               accr = __builtin_amdgcn_mfma_f32_16x16x32_bf16(a1, *(const bf16x8*)(wr_ + 32), accr, 0, 0, 0);
;               acci = __builtin_amdgcn_mfma_f32_16x16x32_bf16(a0, *(const bf16x8*)wi_, acci, 0, 0, 0);
;               acci = __builtin_amdgcn_mfma_f32_16x16x32_bf16(a1, *(const bf16x8*)(wi_ + 32), acci, 0, 0, 0);
;               const int j = jt * 16 + fr;
; #pragma unroll
;               for (int i = 0; i < 4; ++i) { const int t = tt * 16 + fq * 4 + i;
;                   const float r = sigm(accr[i] + gba[jt]), ig = sigm(acci[i] + gbx[jt]), a = __expf(r * gsp[jt]);
;                   As[(d * 64 + t) * 64 + j] = a;
;                   Bs[(d * 64 + t) * 64 + j] = sqrtf(fmaxf(1.0f - a * a, 0.f)) * ig * xcf[t * 65 + j]; }
;           } }
;         __syncthreads();
;         {
;             const int seg = tid >> 7, d = (tid >> 6) & 1, j = tid & 63;
;             float h = 0.f, P = 1.f;
; #pragma unroll
;             for (int s = 0; s < 16; ++s) { const int st = seg * 16 + s, t = d ? 63 - st : st; const float a = As[(d * 64 + t) * 64 + j]; h = a * h + Bs[(d * 64 + t) * 64 + j]; P *= a; }
;             Pq[seg * 128 + (tid & 127)] = P; Hq[seg * 128 + (tid & 127)] = h;
;             __syncthreads();
;             if (PASS == 0) {
;                 if (tid < 128) { float hh = Hq[tid], PP = Pq[tid];
; #pragma unroll
;                     for (int q = 1; q < 4; ++q) { const float pq = Pq[q * 128 + tid]; hh = pq * hh + Hq[q * 128 + tid]; PP *= pq; }
;                     SA[so] = PP; SH[so] = hh; }
	v_mfma_f32_16x16x32_bf16 v[32:35], v[10:13], v[154:157], v[32:35]
	ds_read_b128 v[154:157], v68 offset:50688
	s_waitcnt lgkmcnt(0)
	v_mfma_f32_16x16x32_bf16 v[14:17], v[14:17], v[154:157], 0
	s_nop 4
	v_fmamk_f32 v0, v32, 0xbfb8aa3b, v25
	v_exp_f32_e32 v0, v0
	s_nop 0
	v_mfma_f32_16x16x32_bf16 v[10:13], v[10:13], v[158:161], v[14:17]
	v_add_f32_e32 v0, 1.0, v0
	v_rcp_f32_e32 v0, v0
	s_nop 0
	v_mul_f32_e32 v0, v20, v0
	v_exp_f32_e32 v0, v0
	s_waitcnt vmcnt(0)
	s_nop 1
	v_fmamk_f32 v10, v10, 0xbfb8aa3b, v36
	v_exp_f32_e32 v10, v10
	v_fma_f32 v14, -v0, v0, 1.0
	v_max_f32_e32 v14, 0, v14
	ds_write_b32 v93, v0
	v_add_f32_e32 v10, 1.0, v10
	v_sqrt_f32_e32 v15, v14
	v_rcp_f32_e32 v10, v10
	v_mov_b32_e32 v0, v15
	v_fmamk_f32 v15, v33, 0xbfb8aa3b, v25
	v_exp_f32_e32 v15, v15
	ds_read_b32 v16, v147 offset:8896
	v_add_f32_e32 v14, 1.0, v15
	v_rcp_f32_e32 v14, v14
	v_mul_f32_e32 v0, v10, v0
	s_waitcnt lgkmcnt(0)
	v_mul_f32_e32 v0, v16, v0
	ds_write_b32 v94, v0
	v_mul_f32_e32 v0, v20, v14
	v_exp_f32_e32 v0, v0
	v_fmamk_f32 v10, v11, 0xbfb8aa3b, v36
	v_exp_f32_e32 v10, v10
	v_fma_f32 v11, -v0, v0, 1.0
	v_max_f32_e32 v11, 0, v11
	ds_write_b32 v95, v0
	v_add_f32_e32 v10, 1.0, v10
	v_sqrt_f32_e32 v14, v11
	v_rcp_f32_e32 v10, v10
	v_mov_b32_e32 v0, v14
	v_fmamk_f32 v14, v34, 0xbfb8aa3b, v25
	v_exp_f32_e32 v14, v14
	ds_read_b32 v15, v147 offset:9156
	v_add_f32_e32 v11, 1.0, v14
	v_rcp_f32_e32 v11, v11
	v_mul_f32_e32 v0, v10, v0
	s_waitcnt lgkmcnt(0)
	v_mul_f32_e32 v0, v15, v0
	ds_write_b32 v96, v0
	v_mul_f32_e32 v0, v20, v11
	v_exp_f32_e32 v0, v0
	v_fmamk_f32 v10, v12, 0xbfb8aa3b, v36
	v_exp_f32_e32 v10, v10
	v_fma_f32 v11, -v0, v0, 1.0
	v_max_f32_e32 v11, 0, v11
	ds_write_b32 v97, v0
	v_add_f32_e32 v10, 1.0, v10
	v_sqrt_f32_e32 v12, v11
	v_rcp_f32_e32 v10, v10
	v_mov_b32_e32 v0, v12
	v_fmamk_f32 v12, v35, 0xbfb8aa3b, v25
	v_exp_f32_e32 v12, v12
	ds_read_b32 v14, v147 offset:9416
	v_add_f32_e32 v11, 1.0, v12
	v_rcp_f32_e32 v11, v11
	v_mul_f32_e32 v0, v10, v0
	s_waitcnt lgkmcnt(0)
	v_mul_f32_e32 v0, v14, v0
	ds_write_b32 v98, v0
	v_mul_f32_e32 v0, v20, v11
	v_exp_f32_e32 v0, v0
	v_fmamk_f32 v10, v13, 0xbfb8aa3b, v36
	v_exp_f32_e32 v10, v10
	v_fma_f32 v11, -v0, v0, 1.0
	v_max_f32_e32 v11, 0, v11
	ds_write_b32 v99, v0
	v_add_f32_e32 v10, 1.0, v10
	v_sqrt_f32_e32 v12, v11
	v_rcp_f32_e32 v10, v10
	v_mov_b32_e32 v0, v12
	ds_read_b32 v13, v147 offset:9676
	v_mul_f32_e32 v0, v10, v0
	s_waitcnt lgkmcnt(0)
	v_mul_f32_e32 v0, v0, v13
	ds_write_b32 v100, v0
	s_waitcnt lgkmcnt(0)
	s_barrier
	ds_read_b32 v0, v101
	ds_read_b32 v10, v102
	ds_read_b32 v11, v103
	ds_read_b32 v12, v104
	ds_read_b32 v13, v105
	ds_read_b32 v14, v106
	ds_read_b32 v15, v107
	ds_read_b32 v16, v108
	s_waitcnt lgkmcnt(6)
	v_fmac_f32_e32 v10, 0, v0
	s_waitcnt lgkmcnt(4)
	v_fmac_f32_e32 v12, v10, v11
	v_mul_f32_e32 v0, v0, v11
	s_waitcnt lgkmcnt(2)
	v_fmac_f32_e32 v14, v12, v13
	v_mul_f32_e32 v0, v0, v13
	s_waitcnt lgkmcnt(0)
	v_fmac_f32_e32 v16, v14, v15
	v_mul_f32_e32 v0, v0, v15
	ds_read_b32 v10, v109
	ds_read_b32 v11, v110
	ds_read_b32 v12, v111
	ds_read_b32 v13, v112
	ds_read_b32 v14, v113
	ds_read_b32 v15, v114
	ds_read_b32 v17, v115
	ds_read_b32 v32, v116
	s_waitcnt lgkmcnt(6)
	v_fmac_f32_e32 v11, v16, v10
	v_mul_f32_e32 v0, v0, v10
	s_waitcnt lgkmcnt(4)
	v_fmac_f32_e32 v13, v11, v12
	v_mul_f32_e32 v0, v0, v12
	s_waitcnt lgkmcnt(2)
	v_fmac_f32_e32 v15, v13, v14
	v_mul_f32_e32 v0, v0, v14
	s_waitcnt lgkmcnt(0)
	v_fmac_f32_e32 v32, v15, v17
	v_mul_f32_e32 v0, v0, v17
	ds_read_b32 v10, v117
	ds_read_b32 v11, v118
	ds_read_b32 v12, v119
	ds_read_b32 v13, v120
	ds_read_b32 v14, v121
	ds_read_b32 v15, v122
	ds_read_b32 v16, v123
	ds_read_b32 v17, v124
	s_waitcnt lgkmcnt(6)
	v_fmac_f32_e32 v11, v32, v10
	v_mul_f32_e32 v0, v0, v10
	s_waitcnt lgkmcnt(4)
	v_fmac_f32_e32 v13, v11, v12
	v_mul_f32_e32 v0, v0, v12
	s_waitcnt lgkmcnt(2)
	v_fmac_f32_e32 v15, v13, v14
	v_mul_f32_e32 v0, v0, v14
	s_waitcnt lgkmcnt(0)
	v_fmac_f32_e32 v17, v15, v16
	v_mul_f32_e32 v0, v0, v16
	ds_read_b32 v10, v125
	ds_read_b32 v11, v126
	ds_read_b32 v12, v127
	ds_read_b32 v13, v128
	ds_read_b32 v14, v129
	ds_read_b32 v15, v131
	ds_read_b32 v16, v132
	ds_read_b32 v32, v133
	s_waitcnt lgkmcnt(7)
	v_mul_f32_e32 v0, v0, v10
	s_waitcnt lgkmcnt(6)
	v_fmac_f32_e32 v11, v17, v10
	s_waitcnt lgkmcnt(5)
	v_mul_f32_e32 v0, v0, v12
	s_waitcnt lgkmcnt(4)
	v_fmac_f32_e32 v13, v11, v12
	s_waitcnt lgkmcnt(3)
	v_mul_f32_e32 v0, v0, v14
	s_waitcnt lgkmcnt(2)
	v_fmac_f32_e32 v15, v13, v14
	s_waitcnt lgkmcnt(1)
	v_mul_f32_e32 v0, v0, v16
	s_waitcnt lgkmcnt(0)
	v_fmac_f32_e32 v32, v15, v16
	ds_write_b32 v45, v0
	ds_write_b32 v46, v32
	s_waitcnt lgkmcnt(0)
	s_barrier
	s_and_saveexec_b64 s[40:41], s[38:39]
	s_cbranch_execz .LBB0_295
	ds_read_b32 v0, v46
	ds_read_b32 v12, v45
	ds_read_b32 v13, v134
	ds_read_b32 v14, v135
	s_ashr_i32 s0, s2, 3
	v_and_or_b32 v10, s0, -2, v43
	v_ashrrev_i32_e32 v11, 31, v10
	s_mov_b32 s51, s49
	s_waitcnt lgkmcnt(0)
	v_fmac_f32_e32 v14, v0, v13
	v_mul_f32_e32 v0, v12, v13
	ds_read_b32 v12, v136
	ds_read_b32 v13, v137
	v_lshlrev_b64 v[10:11], 10, v[10:11]
	v_lshl_add_u64 v[10:11], v[10:11], 0, s[50:51]
	v_or_b32_e32 v10, v10, v26
	s_waitcnt lgkmcnt(1)
	v_mul_f32_e32 v0, v0, v12
	s_waitcnt lgkmcnt(0)
	v_fmac_f32_e32 v13, v14, v12
	ds_read_b32 v12, v138
	ds_read_b32 v14, v139
	v_lshlrev_b64 v[10:11], 2, v[10:11]
	s_movk_i32 s23, 0xff7f
	v_readlane_b32 s22, v254, 8
	s_movk_i32 s17, 0x84
	s_mov_b32 s15, 0xfe03f81
	s_movk_i32 s10, 0xc00
	s_waitcnt lgkmcnt(0)
	v_fmac_f32_e32 v14, v13, v12
	v_mul_f32_e32 v0, v0, v12
	v_lshl_add_u64 v[12:13], s[34:35], 0, v[10:11]
	v_lshl_add_u64 v[10:11], s[96:97], 0, v[10:11]
	global_store_dword v[12:13], v0, off
	global_store_dword v[10:11], v14, off
	s_branch .LBB0_295
